# attention units: end-of-unit wait no longer drains the epilogue stores (lgkmcnt(0) only before the barrier), on v37
# baseline (speedup 1.0000x reference)
; #define SBAR() __builtin_amdgcn_sched_barrier(0)
; __device__ __forceinline__ int crow(int r, int hi) { return (r & 3) + 8 * (r >> 2) + 4 * hi; }
; __device__ __forceinline__ void mla_unit(char* lds, const bf16_t* __restrict__ Qp, const bf16_t* __restrict__ Knp, const bf16_t* __restrict__ Vp, ...
;     ...
;   if (hi == 0) li_l[r32] = l_reg; asm volatile("s_waitcnt lgkmcnt(0)" ::: "memory");
;   float rli[16];
; #pragma unroll
;   for (int r = 0; r < 16; ++r) rli[r] = __builtin_amdgcn_rcpf(li_l[crow(r, hi)]);
;   { unsigned zr[16][4];
; #pragma unroll
;     for (int r = 0; r < 16; ++r) { const long trow = wid * QBLK + crow(r, hi);
; #pragma unroll
;       for (int d0 = 0; d0 < 4; ++d0) zr[r][d0] = Zp[trow * LDZ + d0 * 32 + r32]; }
;     asm volatile("s_waitcnt vmcnt(0)" ::: "memory"); SBAR();
.LBB0_235:
	s_or_b64 exec, exec, s[6:7]
	s_waitcnt lgkmcnt(0)
	ds_read_b128 v[66:69], v90
	ds_read_b128 v[70:73], v90 offset:32
	s_lshl_b32 s0, s38, 22
	s_and_b32 s0, s0, 0x3800000
	s_add_u32 s5, s90, s0
	s_waitcnt lgkmcnt(1)
	v_rcp_f32_e32 v171, v66
	v_rcp_f32_e32 v166, v67
	v_rcp_f32_e32 v161, v68
	v_rcp_f32_e32 v155, v69
	ds_read_b128 v[66:69], v90 offset:64
	s_addc_u32 s6, s91, 0
	s_lshl_b64 s[0:1], s[64:65], 9
	s_add_u32 s0, s5, s0
	s_addc_u32 s1, s6, s1
	s_lshl_b32 s5, s69, 8
	s_and_b32 s5, s5, 0x100
	s_add_u32 s6, s0, s5
	s_waitcnt lgkmcnt(0)
	v_rcp_f32_e32 v128, v66
	v_rcp_f32_e32 v122, v67
	v_rcp_f32_e32 v117, v68
	v_rcp_f32_e32 v111, v69
	ds_read_b128 v[66:69], v90 offset:96
	s_addc_u32 s7, s1, 0
	s_lshl_b32 s0, s38, 15
	s_add_u32 s0, s64, s0
	s_addc_u32 s1, s65, 0
	s_lshl_b64 s[0:1], s[0:1], 7
	s_add_u32 s40, s28, s0
	s_waitcnt lgkmcnt(0)
	v_rcp_f32_e32 v105, v66
	v_rcp_f32_e32 v103, v67
	v_or_b32_e32 v98, s39, v195
	v_lshlrev_b32_e32 v66, 1, v196
	v_mov_b32_e32 v67, v0
	s_addc_u32 s41, s29, s1
	v_rcp_f32_e32 v102, v68
	v_rcp_f32_e32 v1, v69
	v_lshl_add_u64 v[68:69], s[6:7], 0, v[66:67]
	s_mov_b64 s[0:1], 0x2000000
	v_ashrrev_i32_e32 v99, 31, v98
	v_lshl_add_u64 v[100:101], v[68:69], 0, s[0:1]
	v_lshlrev_b64 v[68:69], 9, v[98:99]
	v_or_b32_e32 v96, 1, v98
	v_lshl_add_u64 v[68:69], v[100:101], 0, v[68:69]
	v_ashrrev_i32_e32 v97, 31, v96
	global_load_ushort v180, v[68:69], off
	global_load_ushort v177, v[68:69], off offset:64
	global_load_ushort v176, v[68:69], off offset:128
	global_load_ushort v175, v[68:69], off offset:192
	v_lshlrev_b64 v[68:69], 9, v[96:97]
	v_or_b32_e32 v94, 2, v98
	v_lshl_add_u64 v[68:69], v[100:101], 0, v[68:69]
	v_ashrrev_i32_e32 v95, 31, v94
	global_load_ushort v174, v[68:69], off
	global_load_ushort v173, v[68:69], off offset:64
	global_load_ushort v172, v[68:69], off offset:128
	global_load_ushort v170, v[68:69], off offset:192
	v_lshlrev_b64 v[68:69], 9, v[94:95]
	v_or_b32_e32 v92, 3, v98
	v_lshl_add_u64 v[68:69], v[100:101], 0, v[68:69]
	v_ashrrev_i32_e32 v93, 31, v92
	global_load_ushort v169, v[68:69], off
	global_load_ushort v168, v[68:69], off offset:64
	global_load_ushort v167, v[68:69], off offset:128
	global_load_ushort v165, v[68:69], off offset:192
	v_lshlrev_b64 v[68:69], 9, v[92:93]
	v_or_b32_e32 v90, 8, v98
	v_lshl_add_u64 v[68:69], v[100:101], 0, v[68:69]
	v_ashrrev_i32_e32 v91, 31, v90
	global_load_ushort v164, v[68:69], off
	global_load_ushort v163, v[68:69], off offset:64
	global_load_ushort v162, v[68:69], off offset:128
	global_load_ushort v160, v[68:69], off offset:192
	v_lshlrev_b64 v[68:69], 9, v[90:91]
	v_or_b32_e32 v88, 9, v98
	v_lshl_add_u64 v[68:69], v[100:101], 0, v[68:69]
	v_ashrrev_i32_e32 v89, 31, v88
	global_load_ushort v159, v[68:69], off
	global_load_ushort v158, v[68:69], off offset:64
	global_load_ushort v157, v[68:69], off offset:128
	global_load_ushort v156, v[68:69], off offset:192
	v_lshlrev_b64 v[68:69], 9, v[88:89]
	v_or_b32_e32 v86, 10, v98
	v_lshl_add_u64 v[68:69], v[100:101], 0, v[68:69]
	v_ashrrev_i32_e32 v87, 31, v86
	global_load_ushort v154, v[68:69], off
	global_load_ushort v153, v[68:69], off offset:64
	global_load_ushort v152, v[68:69], off offset:128
	global_load_ushort v151, v[68:69], off offset:192
	v_lshlrev_b64 v[68:69], 9, v[86:87]
	v_or_b32_e32 v84, 11, v98
	v_lshl_add_u64 v[68:69], v[100:101], 0, v[68:69]
	v_ashrrev_i32_e32 v85, 31, v84
	global_load_ushort v149, v[68:69], off
	global_load_ushort v148, v[68:69], off offset:64
	global_load_ushort v147, v[68:69], off offset:128
	global_load_ushort v146, v[68:69], off offset:192
	v_lshlrev_b64 v[68:69], 9, v[84:85]
	v_or_b32_e32 v82, 16, v98
	v_lshl_add_u64 v[68:69], v[100:101], 0, v[68:69]
	v_ashrrev_i32_e32 v83, 31, v82
	global_load_ushort v145, v[68:69], off
	global_load_ushort v143, v[68:69], off offset:64
	global_load_ushort v142, v[68:69], off offset:128
	global_load_ushort v141, v[68:69], off offset:192
	v_lshlrev_b64 v[68:69], 9, v[82:83]
	v_or_b32_e32 v80, 17, v98
	v_lshl_add_u64 v[68:69], v[100:101], 0, v[68:69]
	v_ashrrev_i32_e32 v81, 31, v80
	global_load_ushort v140, v[68:69], off
	global_load_ushort v138, v[68:69], off offset:64
	global_load_ushort v137, v[68:69], off offset:128
	global_load_ushort v136, v[68:69], off offset:192
	v_lshlrev_b64 v[68:69], 9, v[80:81]
	v_or_b32_e32 v78, 18, v98
	v_lshl_add_u64 v[68:69], v[100:101], 0, v[68:69]
	v_ashrrev_i32_e32 v79, 31, v78
	global_load_ushort v135, v[68:69], off
	global_load_ushort v134, v[68:69], off offset:64
	global_load_ushort v132, v[68:69], off offset:128
	global_load_ushort v131, v[68:69], off offset:192
	v_lshlrev_b64 v[68:69], 9, v[78:79]
	v_or_b32_e32 v76, 19, v98
	v_lshl_add_u64 v[68:69], v[100:101], 0, v[68:69]
	v_ashrrev_i32_e32 v77, 31, v76
	global_load_ushort v130, v[68:69], off
	global_load_ushort v129, v[68:69], off offset:64
	global_load_ushort v127, v[68:69], off offset:128
	global_load_ushort v126, v[68:69], off offset:192
	v_lshlrev_b64 v[68:69], 9, v[76:77]
	v_or_b32_e32 v74, 24, v98
	v_lshl_add_u64 v[68:69], v[100:101], 0, v[68:69]
	v_ashrrev_i32_e32 v75, 31, v74
	v_rcp_f32_e32 v139, v72
	global_load_ushort v125, v[68:69], off
	global_load_ushort v124, v[68:69], off offset:64
	global_load_ushort v123, v[68:69], off offset:128
	global_load_ushort v121, v[68:69], off offset:192
	v_lshlrev_b64 v[68:69], 9, v[74:75]
	v_or_b32_e32 v72, 25, v98
	v_rcp_f32_e32 v133, v73
	v_lshl_add_u64 v[68:69], v[100:101], 0, v[68:69]
	v_ashrrev_i32_e32 v73, 31, v72
	v_rcp_f32_e32 v150, v70
	global_load_ushort v120, v[68:69], off
	global_load_ushort v119, v[68:69], off offset:64
	global_load_ushort v118, v[68:69], off offset:128
	global_load_ushort v116, v[68:69], off offset:192
	v_lshlrev_b64 v[68:69], 9, v[72:73]
	v_or_b32_e32 v70, 26, v98
	v_rcp_f32_e32 v144, v71
	v_lshl_add_u64 v[68:69], v[100:101], 0, v[68:69]
	v_ashrrev_i32_e32 v71, 31, v70
	global_load_ushort v115, v[68:69], off
	global_load_ushort v114, v[68:69], off offset:64
	global_load_ushort v113, v[68:69], off offset:128
	global_load_ushort v112, v[68:69], off offset:192
	v_lshlrev_b64 v[68:69], 9, v[70:71]
	v_lshl_add_u64 v[68:69], v[100:101], 0, v[68:69]
	global_load_ushort v110, v[68:69], off
	global_load_ushort v109, v[68:69], off offset:64
	global_load_ushort v108, v[68:69], off offset:128
	global_load_ushort v107, v[68:69], off offset:192
	v_or_b32_e32 v68, 27, v98
	v_ashrrev_i32_e32 v69, 31, v68
	v_lshlrev_b64 v[178:179], 9, v[68:69]
	v_lshl_add_u64 v[178:179], v[100:101], 0, v[178:179]
	global_load_ushort v106, v[178:179], off
	global_load_ushort v104, v[178:179], off offset:64
	global_load_ushort v101, v[178:179], off offset:128
	global_load_ushort v100, v[178:179], off offset:192
	s_waitcnt vmcnt(0)
; __device__ __forceinline__ float bf2f(unsigned h) { return __uint_as_float(h << 16); }
; __device__ __forceinline__ unsigned f2bf(float f) { unsigned u = __float_as_uint(f); return (u + 0x7fffu + ((u >> 16) & 1u)) >> 16; }
; __device__ __forceinline__ int crow(int r, int hi) { return (r & 3) + 8 * (r >> 2) + 4 * hi; }
; __device__ __forceinline__ void mla_unit(char* lds, const bf16_t* __restrict__ Qp, const bf16_t* __restrict__ Knp, const bf16_t* __restrict__ Vp, ...
;     ...
; #pragma unroll
;     for (int r = 0; r < 16; ++r) { const long trow = wid * QBLK + crow(r, hi);
; #pragma unroll
;       for (int d0 = 0; d0 < 4; ++d0) { const float z = bf2f(zr[r][d0]); const float v = o[d0][r] * rli[r];
;         const float g = v * z * __builtin_amdgcn_rcpf(1.f + __expf(-z));
;         Op[((size_t)(d0 >> 1) * M_TOK + trow) * 64 + (d0 & 1) * 32 + r32] = (bf16_t)f2bf(g); } } }
	s_waitcnt vmcnt(62)
	v_lshlrev_b32_e32 v178, 16, v180
	v_mul_f32_e32 v50, v50, v171
	v_mul_f32_e32 v50, v50, v178
	v_mul_f32_e32 v178, 0xbfb8aa3b, v178
	v_exp_f32_e32 v178, v178
	v_lshlrev_b64 v[98:99], 7, v[98:99]
	v_lshl_add_u64 v[98:99], s[40:41], 0, v[98:99]
	v_lshl_add_u64 v[98:99], v[98:99], 0, v[66:67]
	v_add_f32_e32 v178, 1.0, v178
	v_rcp_f32_e32 v178, v178
	v_mul_f32_e32 v34, v34, v171
	v_mul_f32_e32 v18, v18, v171
	v_mul_f32_e32 v2, v2, v171
	v_mul_f32_e32 v50, v50, v178
	v_bfe_u32 v178, v50, 16, 1
	v_add3_u32 v50, v50, v178, s63
	global_store_short_d16_hi v[98:99], v50, off
	v_lshlrev_b32_e32 v50, 16, v177
	v_mul_f32_e32 v34, v34, v50
	v_mul_f32_e32 v50, 0xbfb8aa3b, v50
	v_exp_f32_e32 v50, v50
	v_mul_f32_e32 v3, v3, v166
	v_mul_f32_e32 v4, v4, v161
	v_mul_f32_e32 v5, v5, v155
	v_add_f32_e32 v50, 1.0, v50
	v_rcp_f32_e32 v50, v50
	s_mov_b32 s74, s8
	v_mul_f32_e32 v34, v34, v50
	v_bfe_u32 v50, v34, 16, 1
	v_add3_u32 v34, v34, v50, s63
	global_store_short_d16_hi v[98:99], v34, off offset:64
	s_waitcnt vmcnt(62)
	v_lshlrev_b32_e32 v34, 16, v176
	v_mul_f32_e32 v18, v18, v34
	v_mul_f32_e32 v34, 0xbfb8aa3b, v34
	v_exp_f32_e32 v34, v34
	v_add_co_u32_e32 v98, vcc, s93, v98
	v_add_f32_e32 v34, 1.0, v34
	v_rcp_f32_e32 v34, v34
	v_addc_co_u32_e32 v99, vcc, 0, v99, vcc
	v_mul_f32_e32 v18, v18, v34
	v_bfe_u32 v34, v18, 16, 1
	v_add3_u32 v18, v18, v34, s63
	global_store_short_d16_hi v[98:99], v18, off
	v_lshlrev_b32_e32 v18, 16, v175
	v_mul_f32_e32 v2, v2, v18
	v_mul_f32_e32 v18, 0xbfb8aa3b, v18
	v_exp_f32_e32 v18, v18
	s_nop 0
	v_add_f32_e32 v18, 1.0, v18
	v_rcp_f32_e32 v18, v18
	s_nop 0
	v_mul_f32_e32 v2, v2, v18
	v_bfe_u32 v18, v2, 16, 1
	v_add3_u32 v2, v2, v18, s63
	global_store_short_d16_hi v[98:99], v2, off offset:64
	s_waitcnt vmcnt(62)
	v_lshlrev_b32_e32 v2, 16, v174
	v_mul_f32_e32 v18, v51, v166
	v_mul_f32_e32 v18, v18, v2
	v_mul_f32_e32 v2, 0xbfb8aa3b, v2
	v_exp_f32_e32 v2, v2
	v_lshlrev_b64 v[50:51], 7, v[96:97]
	v_lshl_add_u64 v[50:51], s[40:41], 0, v[50:51]
	v_lshl_add_u64 v[50:51], v[50:51], 0, v[66:67]
	v_add_f32_e32 v2, 1.0, v2
	v_rcp_f32_e32 v2, v2
	s_nop 0
	v_mul_f32_e32 v2, v18, v2
	v_bfe_u32 v18, v2, 16, 1
	v_add3_u32 v2, v2, v18, s63
	global_store_short_d16_hi v[50:51], v2, off
	v_lshlrev_b32_e32 v2, 16, v173
	v_mul_f32_e32 v18, v35, v166
	v_mul_f32_e32 v18, v18, v2
	v_mul_f32_e32 v2, 0xbfb8aa3b, v2
	v_exp_f32_e32 v2, v2
	s_nop 0
	v_add_f32_e32 v2, 1.0, v2
	v_rcp_f32_e32 v2, v2
	s_nop 0
	v_mul_f32_e32 v2, v18, v2
	v_bfe_u32 v18, v2, 16, 1
	v_add3_u32 v2, v2, v18, s63
	global_store_short_d16_hi v[50:51], v2, off offset:64
	s_waitcnt vmcnt(62)
	v_lshlrev_b32_e32 v2, 16, v172
	v_mul_f32_e32 v18, v19, v166
	v_mul_f32_e32 v18, v18, v2
	v_mul_f32_e32 v2, 0xbfb8aa3b, v2
	v_exp_f32_e32 v2, v2
	s_nop 0
	v_add_f32_e32 v2, 1.0, v2
	v_rcp_f32_e32 v2, v2
	s_nop 0
	v_mul_f32_e32 v2, v18, v2
	v_bfe_u32 v18, v2, 16, 1
	v_add3_u32 v2, v2, v18, s63
	v_add_co_u32_e32 v18, vcc, s93, v50
	s_nop 1
	v_addc_co_u32_e32 v19, vcc, 0, v51, vcc
	global_store_short_d16_hi v[18:19], v2, off
	v_lshlrev_b32_e32 v2, 16, v170
	v_mul_f32_e32 v3, v3, v2
	v_mul_f32_e32 v2, 0xbfb8aa3b, v2
	v_exp_f32_e32 v2, v2
	s_nop 0
	v_add_f32_e32 v2, 1.0, v2
	v_rcp_f32_e32 v2, v2
	s_nop 0
	v_mul_f32_e32 v2, v3, v2
	v_bfe_u32 v3, v2, 16, 1
	v_add3_u32 v2, v2, v3, s63
	global_store_short_d16_hi v[18:19], v2, off offset:64
	s_waitcnt vmcnt(62)
	v_lshlrev_b32_e32 v2, 16, v169
	v_mul_f32_e32 v3, v52, v161
	v_mul_f32_e32 v3, v3, v2
	v_mul_f32_e32 v2, 0xbfb8aa3b, v2
	v_exp_f32_e32 v2, v2
	v_mul_f32_e32 v19, v36, v161
	v_add_f32_e32 v2, 1.0, v2
	v_rcp_f32_e32 v2, v2
	s_nop 0
	v_mul_f32_e32 v2, v3, v2
	v_bfe_u32 v3, v2, 16, 1
	v_add3_u32 v18, v2, v3, s63
	v_lshlrev_b64 v[2:3], 7, v[94:95]
	v_lshl_add_u64 v[2:3], s[40:41], 0, v[2:3]
	v_lshl_add_u64 v[2:3], v[2:3], 0, v[66:67]
	global_store_short_d16_hi v[2:3], v18, off
	v_lshlrev_b32_e32 v18, 16, v168
	v_mul_f32_e32 v19, v19, v18
	v_mul_f32_e32 v18, 0xbfb8aa3b, v18
	v_exp_f32_e32 v18, v18
	s_nop 0
	v_add_f32_e32 v18, 1.0, v18
	v_rcp_f32_e32 v18, v18
	s_nop 0
	v_mul_f32_e32 v18, v19, v18
	v_bfe_u32 v19, v18, 16, 1
	v_add3_u32 v18, v18, v19, s63
	global_store_short_d16_hi v[2:3], v18, off offset:64
	s_waitcnt vmcnt(62)
	v_lshlrev_b32_e32 v18, 16, v167
	v_mul_f32_e32 v19, v20, v161
	v_mul_f32_e32 v19, v19, v18
	v_mul_f32_e32 v18, 0xbfb8aa3b, v18
	v_exp_f32_e32 v18, v18
	v_add_co_u32_e32 v2, vcc, s93, v2
	v_add_f32_e32 v18, 1.0, v18
	v_rcp_f32_e32 v18, v18
	v_addc_co_u32_e32 v3, vcc, 0, v3, vcc
	v_mul_f32_e32 v18, v19, v18
	v_bfe_u32 v19, v18, 16, 1
	v_add3_u32 v18, v18, v19, s63
	global_store_short_d16_hi v[2:3], v18, off
	v_lshlrev_b32_e32 v18, 16, v165
	v_mul_f32_e32 v4, v4, v18
	v_mul_f32_e32 v18, 0xbfb8aa3b, v18
	v_exp_f32_e32 v18, v18
	s_nop 0
	v_add_f32_e32 v18, 1.0, v18
	v_rcp_f32_e32 v18, v18
	s_nop 0
	v_mul_f32_e32 v4, v4, v18
	v_bfe_u32 v18, v4, 16, 1
	v_add3_u32 v4, v4, v18, s63
	global_store_short_d16_hi v[2:3], v4, off offset:64
	s_waitcnt vmcnt(62)
	v_lshlrev_b32_e32 v2, 16, v164
	v_mul_f32_e32 v3, v53, v155
	v_mul_f32_e32 v3, v3, v2
	v_mul_f32_e32 v2, 0xbfb8aa3b, v2
	v_exp_f32_e32 v2, v2
	v_mul_f32_e32 v18, v37, v155
	v_add_f32_e32 v2, 1.0, v2
	v_rcp_f32_e32 v2, v2
	s_nop 0
	v_mul_f32_e32 v2, v3, v2
	v_bfe_u32 v3, v2, 16, 1
	v_add3_u32 v4, v2, v3, s63
	v_lshlrev_b64 v[2:3], 7, v[92:93]
	v_lshl_add_u64 v[2:3], s[40:41], 0, v[2:3]
	v_lshl_add_u64 v[2:3], v[2:3], 0, v[66:67]
	global_store_short_d16_hi v[2:3], v4, off
	v_lshlrev_b32_e32 v4, 16, v163
	v_mul_f32_e32 v18, v18, v4
	v_mul_f32_e32 v4, 0xbfb8aa3b, v4
	v_exp_f32_e32 v4, v4
	s_nop 0
	v_add_f32_e32 v4, 1.0, v4
	v_rcp_f32_e32 v4, v4
	s_nop 0
	v_mul_f32_e32 v4, v18, v4
	v_bfe_u32 v18, v4, 16, 1
	v_add3_u32 v4, v4, v18, s63
	global_store_short_d16_hi v[2:3], v4, off offset:64
	s_waitcnt vmcnt(62)
; __device__ __forceinline__ float bf2f(unsigned h) { return __uint_as_float(h << 16); }
; __device__ __forceinline__ unsigned f2bf(float f) { unsigned u = __float_as_uint(f); return (u + 0x7fffu + ((u >> 16) & 1u)) >> 16; }
; __device__ __forceinline__ int crow(int r, int hi) { return (r & 3) + 8 * (r >> 2) + 4 * hi; }
; __device__ __forceinline__ void mla_unit(char* lds, const bf16_t* __restrict__ Qp, const bf16_t* __restrict__ Knp, const bf16_t* __restrict__ Vp, ...
;     ...
; #pragma unroll
;     for (int r = 0; r < 16; ++r) { const long trow = wid * QBLK + crow(r, hi);
; #pragma unroll
;       for (int d0 = 0; d0 < 4; ++d0) { const float z = bf2f(zr[r][d0]); const float v = o[d0][r] * rli[r];
;         const float g = v * z * __builtin_amdgcn_rcpf(1.f + __expf(-z));
;         Op[((size_t)(d0 >> 1) * M_TOK + trow) * 64 + (d0 & 1) * 32 + r32] = (bf16_t)f2bf(g); } } }
	v_lshlrev_b32_e32 v4, 16, v162
	v_mul_f32_e32 v18, v21, v155
	v_mul_f32_e32 v18, v18, v4
	v_mul_f32_e32 v4, 0xbfb8aa3b, v4
	v_exp_f32_e32 v4, v4
	v_add_co_u32_e32 v2, vcc, s93, v2
	v_add_f32_e32 v4, 1.0, v4
	v_rcp_f32_e32 v4, v4
	v_addc_co_u32_e32 v3, vcc, 0, v3, vcc
	v_mul_f32_e32 v4, v18, v4
	v_bfe_u32 v18, v4, 16, 1
	v_add3_u32 v4, v4, v18, s63
	global_store_short_d16_hi v[2:3], v4, off
	v_lshlrev_b32_e32 v4, 16, v160
	v_mul_f32_e32 v5, v5, v4
	v_mul_f32_e32 v4, 0xbfb8aa3b, v4
	v_exp_f32_e32 v4, v4
	s_nop 0
	v_add_f32_e32 v4, 1.0, v4
	v_rcp_f32_e32 v4, v4
	s_nop 0
	v_mul_f32_e32 v4, v5, v4
	v_bfe_u32 v5, v4, 16, 1
	v_add3_u32 v4, v4, v5, s63
	global_store_short_d16_hi v[2:3], v4, off offset:64
	s_waitcnt vmcnt(62)
	v_lshlrev_b32_e32 v2, 16, v159
	v_mul_f32_e32 v3, v54, v150
	v_mul_f32_e32 v3, v3, v2
	v_mul_f32_e32 v2, 0xbfb8aa3b, v2
	v_exp_f32_e32 v2, v2
	v_mul_f32_e32 v5, v38, v150
	v_add_f32_e32 v2, 1.0, v2
	v_rcp_f32_e32 v2, v2
	s_nop 0
	v_mul_f32_e32 v2, v3, v2
	v_bfe_u32 v3, v2, 16, 1
	v_add3_u32 v4, v2, v3, s63
	v_lshlrev_b64 v[2:3], 7, v[90:91]
	v_lshl_add_u64 v[2:3], s[40:41], 0, v[2:3]
	v_lshl_add_u64 v[2:3], v[2:3], 0, v[66:67]
	global_store_short_d16_hi v[2:3], v4, off
	v_lshlrev_b32_e32 v4, 16, v158
	v_mul_f32_e32 v5, v5, v4
	v_mul_f32_e32 v4, 0xbfb8aa3b, v4
	v_exp_f32_e32 v4, v4
	s_nop 0
	v_add_f32_e32 v4, 1.0, v4
	v_rcp_f32_e32 v4, v4
	s_nop 0
	v_mul_f32_e32 v4, v5, v4
	v_bfe_u32 v5, v4, 16, 1
	v_add3_u32 v4, v4, v5, s63
	global_store_short_d16_hi v[2:3], v4, off offset:64
	s_waitcnt vmcnt(62)
	v_lshlrev_b32_e32 v4, 16, v157
	v_mul_f32_e32 v5, v22, v150
	v_mul_f32_e32 v5, v5, v4
	v_mul_f32_e32 v4, 0xbfb8aa3b, v4
	v_exp_f32_e32 v4, v4
	v_add_co_u32_e32 v2, vcc, s93, v2
	v_add_f32_e32 v4, 1.0, v4
	v_rcp_f32_e32 v4, v4
	v_addc_co_u32_e32 v3, vcc, 0, v3, vcc
	v_mul_f32_e32 v4, v5, v4
	v_bfe_u32 v5, v4, 16, 1
	v_add3_u32 v4, v4, v5, s63
	global_store_short_d16_hi v[2:3], v4, off
	v_lshlrev_b32_e32 v4, 16, v156
	v_mul_f32_e32 v5, v6, v150
	v_mul_f32_e32 v5, v5, v4
	v_mul_f32_e32 v4, 0xbfb8aa3b, v4
	v_exp_f32_e32 v4, v4
	s_nop 0
	v_add_f32_e32 v4, 1.0, v4
	v_rcp_f32_e32 v4, v4
	s_nop 0
	v_mul_f32_e32 v4, v5, v4
	v_bfe_u32 v5, v4, 16, 1
	v_add3_u32 v4, v4, v5, s63
	global_store_short_d16_hi v[2:3], v4, off offset:64
	s_waitcnt vmcnt(62)
	v_lshlrev_b32_e32 v2, 16, v154
	v_mul_f32_e32 v3, v55, v144
	v_mul_f32_e32 v3, v3, v2
	v_mul_f32_e32 v2, 0xbfb8aa3b, v2
	v_exp_f32_e32 v2, v2
	v_mul_f32_e32 v5, v39, v144
	v_add_f32_e32 v2, 1.0, v2
	v_rcp_f32_e32 v2, v2
	s_nop 0
	v_mul_f32_e32 v2, v3, v2
	v_bfe_u32 v3, v2, 16, 1
	v_add3_u32 v4, v2, v3, s63
	v_lshlrev_b64 v[2:3], 7, v[88:89]
	v_lshl_add_u64 v[2:3], s[40:41], 0, v[2:3]
	v_lshl_add_u64 v[2:3], v[2:3], 0, v[66:67]
	global_store_short_d16_hi v[2:3], v4, off
	v_lshlrev_b32_e32 v4, 16, v153
	v_mul_f32_e32 v5, v5, v4
	v_mul_f32_e32 v4, 0xbfb8aa3b, v4
	v_exp_f32_e32 v4, v4
	s_nop 0
	v_add_f32_e32 v4, 1.0, v4
	v_rcp_f32_e32 v4, v4
	s_nop 0
	v_mul_f32_e32 v4, v5, v4
	v_bfe_u32 v5, v4, 16, 1
	v_add3_u32 v4, v4, v5, s63
	global_store_short_d16_hi v[2:3], v4, off offset:64
	s_waitcnt vmcnt(62)
	v_lshlrev_b32_e32 v4, 16, v152
	v_mul_f32_e32 v5, v23, v144
	v_mul_f32_e32 v5, v5, v4
	v_mul_f32_e32 v4, 0xbfb8aa3b, v4
	v_exp_f32_e32 v4, v4
	v_add_co_u32_e32 v2, vcc, s93, v2
	v_add_f32_e32 v4, 1.0, v4
	v_rcp_f32_e32 v4, v4
	v_addc_co_u32_e32 v3, vcc, 0, v3, vcc
	v_mul_f32_e32 v4, v5, v4
	v_bfe_u32 v5, v4, 16, 1
	v_add3_u32 v4, v4, v5, s63
	global_store_short_d16_hi v[2:3], v4, off
	v_lshlrev_b32_e32 v4, 16, v151
	v_mul_f32_e32 v5, v7, v144
	v_mul_f32_e32 v5, v5, v4
	v_mul_f32_e32 v4, 0xbfb8aa3b, v4
	v_exp_f32_e32 v4, v4
	s_nop 0
	v_add_f32_e32 v4, 1.0, v4
	v_rcp_f32_e32 v4, v4
	s_nop 0
	v_mul_f32_e32 v4, v5, v4
	v_bfe_u32 v5, v4, 16, 1
	v_add3_u32 v4, v4, v5, s63
	global_store_short_d16_hi v[2:3], v4, off offset:64
	s_waitcnt vmcnt(62)
	v_lshlrev_b32_e32 v2, 16, v149
	v_mul_f32_e32 v3, v56, v139
	v_mul_f32_e32 v3, v3, v2
	v_mul_f32_e32 v2, 0xbfb8aa3b, v2
	v_exp_f32_e32 v2, v2
	v_mul_f32_e32 v5, v40, v139
	v_add_f32_e32 v2, 1.0, v2
	v_rcp_f32_e32 v2, v2
	s_nop 0
	v_mul_f32_e32 v2, v3, v2
	v_bfe_u32 v3, v2, 16, 1
	v_add3_u32 v4, v2, v3, s63
	v_lshlrev_b64 v[2:3], 7, v[86:87]
	v_lshl_add_u64 v[2:3], s[40:41], 0, v[2:3]
	v_lshl_add_u64 v[2:3], v[2:3], 0, v[66:67]
	global_store_short_d16_hi v[2:3], v4, off
	v_lshlrev_b32_e32 v4, 16, v148
	v_mul_f32_e32 v5, v5, v4
	v_mul_f32_e32 v4, 0xbfb8aa3b, v4
	v_exp_f32_e32 v4, v4
	s_nop 0
	v_add_f32_e32 v4, 1.0, v4
	v_rcp_f32_e32 v4, v4
	s_nop 0
	v_mul_f32_e32 v4, v5, v4
	v_bfe_u32 v5, v4, 16, 1
	v_add3_u32 v4, v4, v5, s63
	global_store_short_d16_hi v[2:3], v4, off offset:64
	s_waitcnt vmcnt(62)
	v_lshlrev_b32_e32 v4, 16, v147
	v_mul_f32_e32 v5, v24, v139
	v_mul_f32_e32 v5, v5, v4
	v_mul_f32_e32 v4, 0xbfb8aa3b, v4
	v_exp_f32_e32 v4, v4
	v_add_co_u32_e32 v2, vcc, s93, v2
	v_add_f32_e32 v4, 1.0, v4
	v_rcp_f32_e32 v4, v4
	v_addc_co_u32_e32 v3, vcc, 0, v3, vcc
	v_mul_f32_e32 v4, v5, v4
	v_bfe_u32 v5, v4, 16, 1
	v_add3_u32 v4, v4, v5, s63
	global_store_short_d16_hi v[2:3], v4, off
	v_lshlrev_b32_e32 v4, 16, v146
	v_mul_f32_e32 v5, v8, v139
	v_mul_f32_e32 v5, v5, v4
	v_mul_f32_e32 v4, 0xbfb8aa3b, v4
	v_exp_f32_e32 v4, v4
	s_nop 0
	v_add_f32_e32 v4, 1.0, v4
	v_rcp_f32_e32 v4, v4
	s_nop 0
	v_mul_f32_e32 v4, v5, v4
	v_bfe_u32 v5, v4, 16, 1
	v_add3_u32 v4, v4, v5, s63
	global_store_short_d16_hi v[2:3], v4, off offset:64
	s_waitcnt vmcnt(62)
; __device__ __forceinline__ float bf2f(unsigned h) { return __uint_as_float(h << 16); }
; __device__ __forceinline__ unsigned f2bf(float f) { unsigned u = __float_as_uint(f); return (u + 0x7fffu + ((u >> 16) & 1u)) >> 16; }
; __device__ __forceinline__ int crow(int r, int hi) { return (r & 3) + 8 * (r >> 2) + 4 * hi; }
; __device__ __forceinline__ void mla_unit(char* lds, const bf16_t* __restrict__ Qp, const bf16_t* __restrict__ Knp, const bf16_t* __restrict__ Vp, ...
;     ...
; #pragma unroll
;     for (int r = 0; r < 16; ++r) { const long trow = wid * QBLK + crow(r, hi);
; #pragma unroll
;       for (int d0 = 0; d0 < 4; ++d0) { const float z = bf2f(zr[r][d0]); const float v = o[d0][r] * rli[r];
;         const float g = v * z * __builtin_amdgcn_rcpf(1.f + __expf(-z));
;         Op[((size_t)(d0 >> 1) * M_TOK + trow) * 64 + (d0 & 1) * 32 + r32] = (bf16_t)f2bf(g); } } }
	v_lshlrev_b32_e32 v2, 16, v145
	v_mul_f32_e32 v3, v57, v133
	v_mul_f32_e32 v3, v3, v2
	v_mul_f32_e32 v2, 0xbfb8aa3b, v2
	v_exp_f32_e32 v2, v2
	v_mul_f32_e32 v5, v41, v133
	v_add_f32_e32 v2, 1.0, v2
	v_rcp_f32_e32 v2, v2
	s_nop 0
	v_mul_f32_e32 v2, v3, v2
	v_bfe_u32 v3, v2, 16, 1
	v_add3_u32 v4, v2, v3, s63
	v_lshlrev_b64 v[2:3], 7, v[84:85]
	v_lshl_add_u64 v[2:3], s[40:41], 0, v[2:3]
	v_lshl_add_u64 v[2:3], v[2:3], 0, v[66:67]
	global_store_short_d16_hi v[2:3], v4, off
	v_lshlrev_b32_e32 v4, 16, v143
	v_mul_f32_e32 v5, v5, v4
	v_mul_f32_e32 v4, 0xbfb8aa3b, v4
	v_exp_f32_e32 v4, v4
	s_nop 0
	v_add_f32_e32 v4, 1.0, v4
	v_rcp_f32_e32 v4, v4
	s_nop 0
	v_mul_f32_e32 v4, v5, v4
	v_bfe_u32 v5, v4, 16, 1
	v_add3_u32 v4, v4, v5, s63
	global_store_short_d16_hi v[2:3], v4, off offset:64
	s_waitcnt vmcnt(62)
	v_lshlrev_b32_e32 v4, 16, v142
	v_mul_f32_e32 v5, v25, v133
	v_mul_f32_e32 v5, v5, v4
	v_mul_f32_e32 v4, 0xbfb8aa3b, v4
	v_exp_f32_e32 v4, v4
	v_add_co_u32_e32 v2, vcc, s93, v2
	v_add_f32_e32 v4, 1.0, v4
	v_rcp_f32_e32 v4, v4
	v_addc_co_u32_e32 v3, vcc, 0, v3, vcc
	v_mul_f32_e32 v4, v5, v4
	v_bfe_u32 v5, v4, 16, 1
	v_add3_u32 v4, v4, v5, s63
	global_store_short_d16_hi v[2:3], v4, off
	v_lshlrev_b32_e32 v4, 16, v141
	v_mul_f32_e32 v5, v9, v133
	v_mul_f32_e32 v5, v5, v4
	v_mul_f32_e32 v4, 0xbfb8aa3b, v4
	v_exp_f32_e32 v4, v4
	s_nop 0
	v_add_f32_e32 v4, 1.0, v4
	v_rcp_f32_e32 v4, v4
	s_nop 0
	v_mul_f32_e32 v4, v5, v4
	v_bfe_u32 v5, v4, 16, 1
	v_add3_u32 v4, v4, v5, s63
	global_store_short_d16_hi v[2:3], v4, off offset:64
	s_waitcnt vmcnt(62)
	v_lshlrev_b32_e32 v2, 16, v140
	v_mul_f32_e32 v3, v58, v128
	v_mul_f32_e32 v3, v3, v2
	v_mul_f32_e32 v2, 0xbfb8aa3b, v2
	v_exp_f32_e32 v2, v2
	v_mul_f32_e32 v5, v42, v128
	v_add_f32_e32 v2, 1.0, v2
	v_rcp_f32_e32 v2, v2
	s_nop 0
	v_mul_f32_e32 v2, v3, v2
	v_bfe_u32 v3, v2, 16, 1
	v_add3_u32 v4, v2, v3, s63
	v_lshlrev_b64 v[2:3], 7, v[82:83]
	v_lshl_add_u64 v[2:3], s[40:41], 0, v[2:3]
	v_lshl_add_u64 v[2:3], v[2:3], 0, v[66:67]
	global_store_short_d16_hi v[2:3], v4, off
	v_lshlrev_b32_e32 v4, 16, v138
	v_mul_f32_e32 v5, v5, v4
	v_mul_f32_e32 v4, 0xbfb8aa3b, v4
	v_exp_f32_e32 v4, v4
	s_nop 0
	v_add_f32_e32 v4, 1.0, v4
	v_rcp_f32_e32 v4, v4
	s_nop 0
	v_mul_f32_e32 v4, v5, v4
	v_bfe_u32 v5, v4, 16, 1
	v_add3_u32 v4, v4, v5, s63
	global_store_short_d16_hi v[2:3], v4, off offset:64
	s_waitcnt vmcnt(62)
	v_lshlrev_b32_e32 v4, 16, v137
	v_mul_f32_e32 v5, v26, v128
	v_mul_f32_e32 v5, v5, v4
	v_mul_f32_e32 v4, 0xbfb8aa3b, v4
	v_exp_f32_e32 v4, v4
	v_add_co_u32_e32 v2, vcc, s93, v2
	v_add_f32_e32 v4, 1.0, v4
	v_rcp_f32_e32 v4, v4
	v_addc_co_u32_e32 v3, vcc, 0, v3, vcc
	v_mul_f32_e32 v4, v5, v4
	v_bfe_u32 v5, v4, 16, 1
	v_add3_u32 v4, v4, v5, s63
	global_store_short_d16_hi v[2:3], v4, off
	v_lshlrev_b32_e32 v4, 16, v136
	v_mul_f32_e32 v5, v10, v128
	v_mul_f32_e32 v5, v5, v4
	v_mul_f32_e32 v4, 0xbfb8aa3b, v4
	v_exp_f32_e32 v4, v4
	s_nop 0
	v_add_f32_e32 v4, 1.0, v4
	v_rcp_f32_e32 v4, v4
	s_nop 0
	v_mul_f32_e32 v4, v5, v4
	v_bfe_u32 v5, v4, 16, 1
	v_add3_u32 v4, v4, v5, s63
	global_store_short_d16_hi v[2:3], v4, off offset:64
	s_waitcnt vmcnt(62)
	v_lshlrev_b32_e32 v2, 16, v135
	v_mul_f32_e32 v3, v59, v122
	v_mul_f32_e32 v3, v3, v2
	v_mul_f32_e32 v2, 0xbfb8aa3b, v2
	v_exp_f32_e32 v2, v2
	v_mul_f32_e32 v5, v43, v122
	v_add_f32_e32 v2, 1.0, v2
	v_rcp_f32_e32 v2, v2
	s_nop 0
	v_mul_f32_e32 v2, v3, v2
	v_bfe_u32 v3, v2, 16, 1
	v_add3_u32 v4, v2, v3, s63
	v_lshlrev_b64 v[2:3], 7, v[80:81]
	v_lshl_add_u64 v[2:3], s[40:41], 0, v[2:3]
	v_lshl_add_u64 v[2:3], v[2:3], 0, v[66:67]
	global_store_short_d16_hi v[2:3], v4, off
	v_lshlrev_b32_e32 v4, 16, v134
	v_mul_f32_e32 v5, v5, v4
	v_mul_f32_e32 v4, 0xbfb8aa3b, v4
	v_exp_f32_e32 v4, v4
	s_nop 0
	v_add_f32_e32 v4, 1.0, v4
	v_rcp_f32_e32 v4, v4
	s_nop 0
	v_mul_f32_e32 v4, v5, v4
	v_bfe_u32 v5, v4, 16, 1
	v_add3_u32 v4, v4, v5, s63
	global_store_short_d16_hi v[2:3], v4, off offset:64
	s_waitcnt vmcnt(62)
	v_lshlrev_b32_e32 v4, 16, v132
	v_mul_f32_e32 v5, v27, v122
	v_mul_f32_e32 v5, v5, v4
	v_mul_f32_e32 v4, 0xbfb8aa3b, v4
	v_exp_f32_e32 v4, v4
	v_add_co_u32_e32 v2, vcc, s93, v2
	v_add_f32_e32 v4, 1.0, v4
	v_rcp_f32_e32 v4, v4
	v_addc_co_u32_e32 v3, vcc, 0, v3, vcc
	v_mul_f32_e32 v4, v5, v4
	v_bfe_u32 v5, v4, 16, 1
	v_add3_u32 v4, v4, v5, s63
	global_store_short_d16_hi v[2:3], v4, off
	v_lshlrev_b32_e32 v4, 16, v131
	v_mul_f32_e32 v5, v11, v122
	v_mul_f32_e32 v5, v5, v4
	v_mul_f32_e32 v4, 0xbfb8aa3b, v4
	v_exp_f32_e32 v4, v4
	s_nop 0
	v_add_f32_e32 v4, 1.0, v4
	v_rcp_f32_e32 v4, v4
	s_nop 0
	v_mul_f32_e32 v4, v5, v4
	v_bfe_u32 v5, v4, 16, 1
	v_add3_u32 v4, v4, v5, s63
	global_store_short_d16_hi v[2:3], v4, off offset:64
	s_waitcnt vmcnt(62)
	v_lshlrev_b32_e32 v2, 16, v130
	v_mul_f32_e32 v3, v60, v117
	v_mul_f32_e32 v3, v3, v2
	v_mul_f32_e32 v2, 0xbfb8aa3b, v2
	v_exp_f32_e32 v2, v2
	v_mul_f32_e32 v5, v44, v117
	v_add_f32_e32 v2, 1.0, v2
	v_rcp_f32_e32 v2, v2
	s_nop 0
	v_mul_f32_e32 v2, v3, v2
	v_bfe_u32 v3, v2, 16, 1
	v_add3_u32 v4, v2, v3, s63
	v_lshlrev_b64 v[2:3], 7, v[78:79]
	v_lshl_add_u64 v[2:3], s[40:41], 0, v[2:3]
	v_lshl_add_u64 v[2:3], v[2:3], 0, v[66:67]
	global_store_short_d16_hi v[2:3], v4, off
	v_lshlrev_b32_e32 v4, 16, v129
	v_mul_f32_e32 v5, v5, v4
	v_mul_f32_e32 v4, 0xbfb8aa3b, v4
	v_exp_f32_e32 v4, v4
	s_nop 0
	v_add_f32_e32 v4, 1.0, v4
	v_rcp_f32_e32 v4, v4
	s_nop 0
	v_mul_f32_e32 v4, v5, v4
	v_bfe_u32 v5, v4, 16, 1
	v_add3_u32 v4, v4, v5, s63
	global_store_short_d16_hi v[2:3], v4, off offset:64
	s_waitcnt vmcnt(62)
; __device__ __forceinline__ float bf2f(unsigned h) { return __uint_as_float(h << 16); }
; __device__ __forceinline__ unsigned f2bf(float f) { unsigned u = __float_as_uint(f); return (u + 0x7fffu + ((u >> 16) & 1u)) >> 16; }
; __device__ __forceinline__ int crow(int r, int hi) { return (r & 3) + 8 * (r >> 2) + 4 * hi; }
; __device__ __forceinline__ void mla_unit(char* lds, const bf16_t* __restrict__ Qp, const bf16_t* __restrict__ Knp, const bf16_t* __restrict__ Vp, ...
;     ...
; #pragma unroll
;     for (int r = 0; r < 16; ++r) { const long trow = wid * QBLK + crow(r, hi);
; #pragma unroll
;       for (int d0 = 0; d0 < 4; ++d0) { const float z = bf2f(zr[r][d0]); const float v = o[d0][r] * rli[r];
;         const float g = v * z * __builtin_amdgcn_rcpf(1.f + __expf(-z));
;         Op[((size_t)(d0 >> 1) * M_TOK + trow) * 64 + (d0 & 1) * 32 + r32] = (bf16_t)f2bf(g); } } }
	v_lshlrev_b32_e32 v4, 16, v127
	v_mul_f32_e32 v5, v28, v117
	v_mul_f32_e32 v5, v5, v4
	v_mul_f32_e32 v4, 0xbfb8aa3b, v4
	v_exp_f32_e32 v4, v4
	v_add_co_u32_e32 v2, vcc, s93, v2
	v_add_f32_e32 v4, 1.0, v4
	v_rcp_f32_e32 v4, v4
	v_addc_co_u32_e32 v3, vcc, 0, v3, vcc
	v_mul_f32_e32 v4, v5, v4
	v_bfe_u32 v5, v4, 16, 1
	v_add3_u32 v4, v4, v5, s63
	global_store_short_d16_hi v[2:3], v4, off
	v_lshlrev_b32_e32 v4, 16, v126
	v_mul_f32_e32 v5, v12, v117
	v_mul_f32_e32 v5, v5, v4
	v_mul_f32_e32 v4, 0xbfb8aa3b, v4
	v_exp_f32_e32 v4, v4
	s_nop 0
	v_add_f32_e32 v4, 1.0, v4
	v_rcp_f32_e32 v4, v4
	s_nop 0
	v_mul_f32_e32 v4, v5, v4
	v_bfe_u32 v5, v4, 16, 1
	v_add3_u32 v4, v4, v5, s63
	global_store_short_d16_hi v[2:3], v4, off offset:64
	s_waitcnt vmcnt(62)
	v_lshlrev_b32_e32 v2, 16, v125
	v_mul_f32_e32 v3, v61, v111
	v_mul_f32_e32 v3, v3, v2
	v_mul_f32_e32 v2, 0xbfb8aa3b, v2
	v_exp_f32_e32 v2, v2
	v_mul_f32_e32 v5, v45, v111
	v_add_f32_e32 v2, 1.0, v2
	v_rcp_f32_e32 v2, v2
	s_nop 0
	v_mul_f32_e32 v2, v3, v2
	v_bfe_u32 v3, v2, 16, 1
	v_add3_u32 v4, v2, v3, s63
	v_lshlrev_b64 v[2:3], 7, v[76:77]
	v_lshl_add_u64 v[2:3], s[40:41], 0, v[2:3]
	v_lshl_add_u64 v[2:3], v[2:3], 0, v[66:67]
	global_store_short_d16_hi v[2:3], v4, off
	v_lshlrev_b32_e32 v4, 16, v124
	v_mul_f32_e32 v5, v5, v4
	v_mul_f32_e32 v4, 0xbfb8aa3b, v4
	v_exp_f32_e32 v4, v4
	s_nop 0
	v_add_f32_e32 v4, 1.0, v4
	v_rcp_f32_e32 v4, v4
	s_nop 0
	v_mul_f32_e32 v4, v5, v4
	v_bfe_u32 v5, v4, 16, 1
	v_add3_u32 v4, v4, v5, s63
	global_store_short_d16_hi v[2:3], v4, off offset:64
	s_waitcnt vmcnt(62)
	v_lshlrev_b32_e32 v4, 16, v123
	v_mul_f32_e32 v5, v29, v111
	v_mul_f32_e32 v5, v5, v4
	v_mul_f32_e32 v4, 0xbfb8aa3b, v4
	v_exp_f32_e32 v4, v4
	v_add_co_u32_e32 v2, vcc, s93, v2
	v_add_f32_e32 v4, 1.0, v4
	v_rcp_f32_e32 v4, v4
	v_addc_co_u32_e32 v3, vcc, 0, v3, vcc
	v_mul_f32_e32 v4, v5, v4
	v_bfe_u32 v5, v4, 16, 1
	v_add3_u32 v4, v4, v5, s63
	global_store_short_d16_hi v[2:3], v4, off
	v_lshlrev_b32_e32 v4, 16, v121
	v_mul_f32_e32 v5, v13, v111
	v_mul_f32_e32 v5, v5, v4
	v_mul_f32_e32 v4, 0xbfb8aa3b, v4
	v_exp_f32_e32 v4, v4
	s_nop 0
	v_add_f32_e32 v4, 1.0, v4
	v_rcp_f32_e32 v4, v4
	s_nop 0
	v_mul_f32_e32 v4, v5, v4
	v_bfe_u32 v5, v4, 16, 1
	v_add3_u32 v4, v4, v5, s63
	global_store_short_d16_hi v[2:3], v4, off offset:64
	s_waitcnt vmcnt(62)
	v_lshlrev_b32_e32 v2, 16, v120
	v_mul_f32_e32 v3, v62, v105
	v_mul_f32_e32 v3, v3, v2
	v_mul_f32_e32 v2, 0xbfb8aa3b, v2
	v_exp_f32_e32 v2, v2
	v_mul_f32_e32 v5, v46, v105
	v_add_f32_e32 v2, 1.0, v2
	v_rcp_f32_e32 v2, v2
	s_nop 0
	v_mul_f32_e32 v2, v3, v2
	v_bfe_u32 v3, v2, 16, 1
	v_add3_u32 v4, v2, v3, s63
	v_lshlrev_b64 v[2:3], 7, v[74:75]
	v_lshl_add_u64 v[2:3], s[40:41], 0, v[2:3]
	v_lshl_add_u64 v[2:3], v[2:3], 0, v[66:67]
	global_store_short_d16_hi v[2:3], v4, off
	v_lshlrev_b32_e32 v4, 16, v119
	v_mul_f32_e32 v5, v5, v4
	v_mul_f32_e32 v4, 0xbfb8aa3b, v4
	v_exp_f32_e32 v4, v4
	s_nop 0
	v_add_f32_e32 v4, 1.0, v4
	v_rcp_f32_e32 v4, v4
	s_nop 0
	v_mul_f32_e32 v4, v5, v4
	v_bfe_u32 v5, v4, 16, 1
	v_add3_u32 v4, v4, v5, s63
	global_store_short_d16_hi v[2:3], v4, off offset:64
	s_waitcnt vmcnt(62)
	v_lshlrev_b32_e32 v4, 16, v118
	v_mul_f32_e32 v5, v30, v105
	v_mul_f32_e32 v5, v5, v4
	v_mul_f32_e32 v4, 0xbfb8aa3b, v4
	v_exp_f32_e32 v4, v4
	v_add_co_u32_e32 v2, vcc, s93, v2
	v_add_f32_e32 v4, 1.0, v4
	v_rcp_f32_e32 v4, v4
	v_addc_co_u32_e32 v3, vcc, 0, v3, vcc
	v_mul_f32_e32 v4, v5, v4
	v_bfe_u32 v5, v4, 16, 1
	v_add3_u32 v4, v4, v5, s63
	global_store_short_d16_hi v[2:3], v4, off
	v_lshlrev_b32_e32 v4, 16, v116
	v_mul_f32_e32 v5, v14, v105
	v_mul_f32_e32 v5, v5, v4
	v_mul_f32_e32 v4, 0xbfb8aa3b, v4
	v_exp_f32_e32 v4, v4
	s_nop 0
	v_add_f32_e32 v4, 1.0, v4
	v_rcp_f32_e32 v4, v4
	s_nop 0
	v_mul_f32_e32 v4, v5, v4
	v_bfe_u32 v5, v4, 16, 1
	v_add3_u32 v4, v4, v5, s63
	global_store_short_d16_hi v[2:3], v4, off offset:64
	s_waitcnt vmcnt(62)
	v_lshlrev_b32_e32 v2, 16, v115
	v_mul_f32_e32 v3, v63, v103
	v_mul_f32_e32 v3, v3, v2
	v_mul_f32_e32 v2, 0xbfb8aa3b, v2
	v_exp_f32_e32 v2, v2
	v_mul_f32_e32 v5, v47, v103
	v_add_f32_e32 v2, 1.0, v2
	v_rcp_f32_e32 v2, v2
	s_nop 0
	v_mul_f32_e32 v2, v3, v2
	v_bfe_u32 v3, v2, 16, 1
	v_add3_u32 v4, v2, v3, s63
	v_lshlrev_b64 v[2:3], 7, v[72:73]
	v_lshl_add_u64 v[2:3], s[40:41], 0, v[2:3]
	v_lshl_add_u64 v[2:3], v[2:3], 0, v[66:67]
	global_store_short_d16_hi v[2:3], v4, off
	v_lshlrev_b32_e32 v4, 16, v114
	v_mul_f32_e32 v5, v5, v4
	v_mul_f32_e32 v4, 0xbfb8aa3b, v4
	v_exp_f32_e32 v4, v4
	s_nop 0
	v_add_f32_e32 v4, 1.0, v4
	v_rcp_f32_e32 v4, v4
	s_nop 0
	v_mul_f32_e32 v4, v5, v4
	v_bfe_u32 v5, v4, 16, 1
	v_add3_u32 v4, v4, v5, s63
	global_store_short_d16_hi v[2:3], v4, off offset:64
	s_waitcnt vmcnt(62)
; __device__ __forceinline__ float bf2f(unsigned h) { return __uint_as_float(h << 16); }
; __device__ __forceinline__ unsigned f2bf(float f) { unsigned u = __float_as_uint(f); return (u + 0x7fffu + ((u >> 16) & 1u)) >> 16; }
; __device__ __forceinline__ int crow(int r, int hi) { return (r & 3) + 8 * (r >> 2) + 4 * hi; }
; __device__ __forceinline__ void mla_unit(char* lds, const bf16_t* __restrict__ Qp, const bf16_t* __restrict__ Knp, const bf16_t* __restrict__ Vp, ...
;     ...
; #pragma unroll
;     for (int r = 0; r < 16; ++r) { const long trow = wid * QBLK + crow(r, hi);
; #pragma unroll
;       for (int d0 = 0; d0 < 4; ++d0) { const float z = bf2f(zr[r][d0]); const float v = o[d0][r] * rli[r];
;         const float g = v * z * __builtin_amdgcn_rcpf(1.f + __expf(-z));
;         Op[((size_t)(d0 >> 1) * M_TOK + trow) * 64 + (d0 & 1) * 32 + r32] = (bf16_t)f2bf(g); } } }
;   asm volatile("s_waitcnt vmcnt(0) lgkmcnt(0)\n\ts_barrier" ::: "memory");
	v_lshlrev_b32_e32 v4, 16, v113
	v_mul_f32_e32 v5, v31, v103
	v_mul_f32_e32 v5, v5, v4
	v_mul_f32_e32 v4, 0xbfb8aa3b, v4
	v_exp_f32_e32 v4, v4
	v_add_co_u32_e32 v2, vcc, s93, v2
	v_add_f32_e32 v4, 1.0, v4
	v_rcp_f32_e32 v4, v4
	v_addc_co_u32_e32 v3, vcc, 0, v3, vcc
	v_mul_f32_e32 v4, v5, v4
	v_bfe_u32 v5, v4, 16, 1
	v_add3_u32 v4, v4, v5, s63
	global_store_short_d16_hi v[2:3], v4, off
	v_lshlrev_b32_e32 v4, 16, v112
	v_mul_f32_e32 v5, v15, v103
	v_mul_f32_e32 v5, v5, v4
	v_mul_f32_e32 v4, 0xbfb8aa3b, v4
	v_exp_f32_e32 v4, v4
	s_nop 0
	v_add_f32_e32 v4, 1.0, v4
	v_rcp_f32_e32 v4, v4
	s_nop 0
	v_mul_f32_e32 v4, v5, v4
	v_bfe_u32 v5, v4, 16, 1
	v_add3_u32 v4, v4, v5, s63
	global_store_short_d16_hi v[2:3], v4, off offset:64
	s_waitcnt vmcnt(62)
	v_lshlrev_b32_e32 v2, 16, v110
	v_mul_f32_e32 v3, v64, v102
	v_mul_f32_e32 v3, v3, v2
	v_mul_f32_e32 v2, 0xbfb8aa3b, v2
	v_exp_f32_e32 v2, v2
	v_mul_f32_e32 v5, v48, v102
	v_add_f32_e32 v2, 1.0, v2
	v_rcp_f32_e32 v2, v2
	s_nop 0
	v_mul_f32_e32 v2, v3, v2
	v_bfe_u32 v3, v2, 16, 1
	v_add3_u32 v4, v2, v3, s63
	v_lshlrev_b64 v[2:3], 7, v[70:71]
	v_lshl_add_u64 v[2:3], s[40:41], 0, v[2:3]
	v_lshl_add_u64 v[2:3], v[2:3], 0, v[66:67]
	global_store_short_d16_hi v[2:3], v4, off
	v_lshlrev_b32_e32 v4, 16, v109
	v_mul_f32_e32 v5, v5, v4
	v_mul_f32_e32 v4, 0xbfb8aa3b, v4
	v_exp_f32_e32 v4, v4
	s_nop 0
	v_add_f32_e32 v4, 1.0, v4
	v_rcp_f32_e32 v4, v4
	s_nop 0
	v_mul_f32_e32 v4, v5, v4
	v_bfe_u32 v5, v4, 16, 1
	v_add3_u32 v4, v4, v5, s63
	global_store_short_d16_hi v[2:3], v4, off offset:64
	s_waitcnt vmcnt(62)
	v_lshlrev_b32_e32 v4, 16, v108
	v_mul_f32_e32 v5, v32, v102
	v_mul_f32_e32 v5, v5, v4
	v_mul_f32_e32 v4, 0xbfb8aa3b, v4
	v_exp_f32_e32 v4, v4
	v_add_co_u32_e32 v2, vcc, s93, v2
	v_add_f32_e32 v4, 1.0, v4
	v_rcp_f32_e32 v4, v4
	v_addc_co_u32_e32 v3, vcc, 0, v3, vcc
	v_mul_f32_e32 v4, v5, v4
	v_bfe_u32 v5, v4, 16, 1
	v_add3_u32 v4, v4, v5, s63
	global_store_short_d16_hi v[2:3], v4, off
	v_lshlrev_b32_e32 v4, 16, v107
	v_mul_f32_e32 v5, v16, v102
	v_mul_f32_e32 v5, v5, v4
	v_mul_f32_e32 v4, 0xbfb8aa3b, v4
	v_exp_f32_e32 v4, v4
	s_nop 0
	v_add_f32_e32 v4, 1.0, v4
	v_rcp_f32_e32 v4, v4
	s_nop 0
	v_mul_f32_e32 v4, v5, v4
	v_bfe_u32 v5, v4, 16, 1
	v_add3_u32 v4, v4, v5, s63
	global_store_short_d16_hi v[2:3], v4, off offset:64
	s_waitcnt vmcnt(62)
	v_lshlrev_b32_e32 v2, 16, v106
	v_mul_f32_e32 v3, v65, v1
	v_mul_f32_e32 v3, v3, v2
	v_mul_f32_e32 v2, 0xbfb8aa3b, v2
	v_exp_f32_e32 v2, v2
	v_mul_f32_e32 v5, v49, v1
	v_add_f32_e32 v2, 1.0, v2
	v_rcp_f32_e32 v2, v2
	s_nop 0
	v_mul_f32_e32 v2, v3, v2
	v_bfe_u32 v3, v2, 16, 1
	v_add3_u32 v4, v2, v3, s63
	v_lshlrev_b64 v[2:3], 7, v[68:69]
	v_lshl_add_u64 v[2:3], s[40:41], 0, v[2:3]
	v_lshl_add_u64 v[2:3], v[2:3], 0, v[66:67]
	global_store_short_d16_hi v[2:3], v4, off
	v_lshlrev_b32_e32 v4, 16, v104
	v_mul_f32_e32 v5, v5, v4
	v_mul_f32_e32 v4, 0xbfb8aa3b, v4
	v_exp_f32_e32 v4, v4
	s_nop 0
	v_add_f32_e32 v4, 1.0, v4
	v_rcp_f32_e32 v4, v4
	s_nop 0
	v_mul_f32_e32 v4, v5, v4
	v_bfe_u32 v5, v4, 16, 1
	v_add3_u32 v4, v4, v5, s63
	global_store_short_d16_hi v[2:3], v4, off offset:64
	s_waitcnt vmcnt(62)
	v_lshlrev_b32_e32 v4, 16, v101
	v_mul_f32_e32 v5, v33, v1
	v_mul_f32_e32 v5, v5, v4
	v_mul_f32_e32 v4, 0xbfb8aa3b, v4
	v_exp_f32_e32 v4, v4
	v_add_co_u32_e32 v2, vcc, s93, v2
	v_mul_f32_e32 v1, v17, v1
	v_add_f32_e32 v4, 1.0, v4
	v_rcp_f32_e32 v4, v4
	v_addc_co_u32_e32 v3, vcc, 0, v3, vcc
	s_and_b64 vcc, exec, s[42:43]
	v_mul_f32_e32 v4, v5, v4
	v_bfe_u32 v5, v4, 16, 1
	v_add3_u32 v4, v4, v5, s63
	global_store_short_d16_hi v[2:3], v4, off
	v_lshlrev_b32_e32 v4, 16, v100
	v_mul_f32_e32 v1, v1, v4
	v_mul_f32_e32 v4, 0xbfb8aa3b, v4
	v_exp_f32_e32 v4, v4
	s_nop 0
	v_add_f32_e32 v4, 1.0, v4
	v_rcp_f32_e32 v4, v4
	s_nop 0
	v_mul_f32_e32 v1, v1, v4
	v_bfe_u32 v4, v1, 16, 1
	v_add3_u32 v1, v1, v4, s63
	global_store_short_d16_hi v[2:3], v1, off offset:64
	s_setprio 0
	s_waitcnt lgkmcnt(0)
	s_barrier
	s_cbranch_vccnz .LBB0_271

; #define SBAR() __builtin_amdgcn_sched_barrier(0)
; __device__ __forceinline__ int crow(int r, int hi) { return (r & 3) + 8 * (r >> 2) + 4 * hi; }
; __device__ __forceinline__ void na_unit3(char* lds, const bf16_t* __restrict__ Qp, const bf16_t* __restrict__ Knp, const bf16_t* __restrict__ Vp, ...
;     ...
;   if (hi == 0) li_l[r32] = l_reg; asm volatile("s_waitcnt lgkmcnt(0)" ::: "memory");
;   float rli[16];
; #pragma unroll
;   for (int r = 0; r < 16; ++r) rli[r] = __builtin_amdgcn_rcpf(li_l[crow(r, hi)]);
;   { unsigned zr[16][4];
; #pragma unroll
;     for (int r = 0; r < 16; ++r) { const long trow = wid * QBLK + crow(r, hi);
; #pragma unroll
;       for (int d0 = 0; d0 < 4; ++d0) zr[r][d0] = Zp[trow * LDZ + d0 * 32 + r32]; }
;     asm volatile("s_waitcnt vmcnt(0)" ::: "memory"); SBAR();
.LBB0_275:
	s_or_b64 exec, exec, s[6:7]
	s_waitcnt lgkmcnt(0)
	v_lshl_add_u32 v1, v222, 4, s26
	ds_read_b128 v[2:5], v1
	ds_read_b128 v[6:9], v1 offset:32
	s_lshl_b64 s[0:1], s[82:83], 1
	s_add_u32 s6, s81, s0
	s_addc_u32 s7, s84, s1
	s_waitcnt lgkmcnt(1)
	v_rcp_f32_e32 v171, v2
	v_rcp_f32_e32 v166, v3
	v_rcp_f32_e32 v161, v4
	v_rcp_f32_e32 v155, v5
	ds_read_b128 v[2:5], v1 offset:64
	s_lshl_b32 s0, s77, 15
	s_add_u32 s0, s34, s0
	s_addc_u32 s1, s35, 0
	s_lshl_b64 s[0:1], s[0:1], 7
	s_waitcnt lgkmcnt(0)
	v_rcp_f32_e32 v128, v2
	v_rcp_f32_e32 v122, v3
	v_rcp_f32_e32 v117, v4
	v_rcp_f32_e32 v111, v5
	ds_read_b128 v[2:5], v1 offset:96
	s_add_u32 s34, s28, s0
	v_lshl_or_b32 v98, v222, 2, s80
	s_addc_u32 s35, s29, s1
	s_mov_b64 s[0:1], 0xc000000
	s_waitcnt lgkmcnt(0)
	v_rcp_f32_e32 v105, v2
	v_rcp_f32_e32 v103, v3
	v_lshlrev_b32_e32 v2, 1, v221
	v_mov_b32_e32 v3, v0
	v_rcp_f32_e32 v102, v4
	v_rcp_f32_e32 v1, v5
	v_lshl_add_u64 v[4:5], s[6:7], 0, v[2:3]
	v_ashrrev_i32_e32 v99, 31, v98
	v_lshl_add_u64 v[100:101], v[4:5], 0, s[0:1]
	v_lshlrev_b64 v[4:5], 9, v[98:99]
	v_or_b32_e32 v96, 1, v98
	v_lshl_add_u64 v[4:5], v[100:101], 0, v[4:5]
	v_ashrrev_i32_e32 v97, 31, v96
	global_load_ushort v180, v[4:5], off
	global_load_ushort v177, v[4:5], off offset:64
	global_load_ushort v176, v[4:5], off offset:128
	global_load_ushort v175, v[4:5], off offset:192
	v_lshlrev_b64 v[4:5], 9, v[96:97]
	v_or_b32_e32 v94, 2, v98
	v_lshl_add_u64 v[4:5], v[100:101], 0, v[4:5]
	v_ashrrev_i32_e32 v95, 31, v94
	global_load_ushort v174, v[4:5], off
	global_load_ushort v173, v[4:5], off offset:64
	global_load_ushort v172, v[4:5], off offset:128
	global_load_ushort v170, v[4:5], off offset:192
	v_lshlrev_b64 v[4:5], 9, v[94:95]
	v_or_b32_e32 v92, 3, v98
	v_lshl_add_u64 v[4:5], v[100:101], 0, v[4:5]
	v_ashrrev_i32_e32 v93, 31, v92
	global_load_ushort v169, v[4:5], off
	global_load_ushort v168, v[4:5], off offset:64
	global_load_ushort v167, v[4:5], off offset:128
	global_load_ushort v165, v[4:5], off offset:192
	v_lshlrev_b64 v[4:5], 9, v[92:93]
	v_or_b32_e32 v90, 8, v98
	v_lshl_add_u64 v[4:5], v[100:101], 0, v[4:5]
	v_ashrrev_i32_e32 v91, 31, v90
	global_load_ushort v164, v[4:5], off
	global_load_ushort v163, v[4:5], off offset:64
	global_load_ushort v162, v[4:5], off offset:128
	global_load_ushort v160, v[4:5], off offset:192
	v_lshlrev_b64 v[4:5], 9, v[90:91]
	v_or_b32_e32 v88, 9, v98
	v_lshl_add_u64 v[4:5], v[100:101], 0, v[4:5]
	v_ashrrev_i32_e32 v89, 31, v88
	global_load_ushort v159, v[4:5], off
	global_load_ushort v158, v[4:5], off offset:64
	global_load_ushort v157, v[4:5], off offset:128
	global_load_ushort v156, v[4:5], off offset:192
	v_lshlrev_b64 v[4:5], 9, v[88:89]
	v_or_b32_e32 v86, 10, v98
	v_lshl_add_u64 v[4:5], v[100:101], 0, v[4:5]
	v_ashrrev_i32_e32 v87, 31, v86
	global_load_ushort v154, v[4:5], off
	global_load_ushort v153, v[4:5], off offset:64
	global_load_ushort v152, v[4:5], off offset:128
	global_load_ushort v151, v[4:5], off offset:192
	v_lshlrev_b64 v[4:5], 9, v[86:87]
	v_or_b32_e32 v84, 11, v98
	v_lshl_add_u64 v[4:5], v[100:101], 0, v[4:5]
	v_ashrrev_i32_e32 v85, 31, v84
	global_load_ushort v150, v[4:5], off
	global_load_ushort v148, v[4:5], off offset:64
	global_load_ushort v147, v[4:5], off offset:128
	global_load_ushort v146, v[4:5], off offset:192
	v_lshlrev_b64 v[4:5], 9, v[84:85]
	v_or_b32_e32 v82, 16, v98
	v_lshl_add_u64 v[4:5], v[100:101], 0, v[4:5]
	v_ashrrev_i32_e32 v83, 31, v82
	global_load_ushort v145, v[4:5], off
	global_load_ushort v143, v[4:5], off offset:64
	global_load_ushort v142, v[4:5], off offset:128
	global_load_ushort v141, v[4:5], off offset:192
	v_lshlrev_b64 v[4:5], 9, v[82:83]
	v_or_b32_e32 v80, 17, v98
	v_lshl_add_u64 v[4:5], v[100:101], 0, v[4:5]
	v_ashrrev_i32_e32 v81, 31, v80
	global_load_ushort v140, v[4:5], off
	global_load_ushort v138, v[4:5], off offset:64
	global_load_ushort v137, v[4:5], off offset:128
	global_load_ushort v136, v[4:5], off offset:192
	v_lshlrev_b64 v[4:5], 9, v[80:81]
	v_or_b32_e32 v14, 18, v98
	v_lshl_add_u64 v[4:5], v[100:101], 0, v[4:5]
	v_ashrrev_i32_e32 v15, 31, v14
	global_load_ushort v135, v[4:5], off
	global_load_ushort v134, v[4:5], off offset:64
	global_load_ushort v132, v[4:5], off offset:128
	global_load_ushort v131, v[4:5], off offset:192
	v_lshlrev_b64 v[4:5], 9, v[14:15]
	v_or_b32_e32 v12, 19, v98
	v_lshl_add_u64 v[4:5], v[100:101], 0, v[4:5]
	v_ashrrev_i32_e32 v13, 31, v12
	global_load_ushort v130, v[4:5], off
	global_load_ushort v129, v[4:5], off offset:64
	global_load_ushort v127, v[4:5], off offset:128
	global_load_ushort v126, v[4:5], off offset:192
	v_lshlrev_b64 v[4:5], 9, v[12:13]
	v_or_b32_e32 v10, 24, v98
	v_lshl_add_u64 v[4:5], v[100:101], 0, v[4:5]
	v_ashrrev_i32_e32 v11, 31, v10
	v_rcp_f32_e32 v139, v8
	global_load_ushort v125, v[4:5], off
	global_load_ushort v124, v[4:5], off offset:64
	global_load_ushort v123, v[4:5], off offset:128
	global_load_ushort v121, v[4:5], off offset:192
	v_lshlrev_b64 v[4:5], 9, v[10:11]
	v_or_b32_e32 v8, 25, v98
	v_rcp_f32_e32 v133, v9
	v_lshl_add_u64 v[4:5], v[100:101], 0, v[4:5]
	v_ashrrev_i32_e32 v9, 31, v8
	v_rcp_f32_e32 v149, v6
	global_load_ushort v120, v[4:5], off
	global_load_ushort v119, v[4:5], off offset:64
	global_load_ushort v118, v[4:5], off offset:128
	global_load_ushort v116, v[4:5], off offset:192
	v_lshlrev_b64 v[4:5], 9, v[8:9]
	v_or_b32_e32 v6, 26, v98
	v_rcp_f32_e32 v144, v7
	v_lshl_add_u64 v[4:5], v[100:101], 0, v[4:5]
	v_ashrrev_i32_e32 v7, 31, v6
	global_load_ushort v115, v[4:5], off
	global_load_ushort v114, v[4:5], off offset:64
	global_load_ushort v113, v[4:5], off offset:128
	global_load_ushort v112, v[4:5], off offset:192
	v_lshlrev_b64 v[4:5], 9, v[6:7]
	v_lshl_add_u64 v[4:5], v[100:101], 0, v[4:5]
	global_load_ushort v110, v[4:5], off
	global_load_ushort v109, v[4:5], off offset:64
	global_load_ushort v108, v[4:5], off offset:128
	global_load_ushort v107, v[4:5], off offset:192
	v_or_b32_e32 v4, 27, v98
	v_ashrrev_i32_e32 v5, 31, v4
	v_lshlrev_b64 v[178:179], 9, v[4:5]
	v_lshl_add_u64 v[178:179], v[100:101], 0, v[178:179]
	global_load_ushort v106, v[178:179], off
	global_load_ushort v104, v[178:179], off offset:64
	global_load_ushort v101, v[178:179], off offset:128
	global_load_ushort v100, v[178:179], off offset:192
	s_waitcnt vmcnt(0)
; __device__ __forceinline__ float bf2f(unsigned h) { return __uint_as_float(h << 16); }
; __device__ __forceinline__ unsigned f2bf(float f) { unsigned u = __float_as_uint(f); return (u + 0x7fffu + ((u >> 16) & 1u)) >> 16; }
; __device__ __forceinline__ int crow(int r, int hi) { return (r & 3) + 8 * (r >> 2) + 4 * hi; }
; __device__ __forceinline__ void na_unit3(char* lds, const bf16_t* __restrict__ Qp, const bf16_t* __restrict__ Knp, const bf16_t* __restrict__ Vp, ...
;     ...
;     for (int r = 0; r < 16; ++r) { const long trow = wid * QBLK + crow(r, hi);
; #pragma unroll
;       for (int d0 = 0; d0 < 4; ++d0) { const float z = bf2f(zr[r][d0]); const float v = o[d0][r] * rli[r];
;         const float g = v * z * __builtin_amdgcn_rcpf(1.f + __expf(-z));
;         Op[((size_t)(d0 >> 1) * M_TOK + trow) * 64 + (d0 & 1) * 32 + r32] = (bf16_t)f2bf(g); } } }
; __global__ void __launch_bounds__(NWAVES * 64, 2) fwd_mega(Args args) {
;     ...
;             for (int rep = 0; rep < REP_NA; ++rep) for (int u = vcu; u < 1024; u += G) {
	s_waitcnt vmcnt(62)
	v_lshlrev_b32_e32 v178, 16, v180
	v_mul_f32_e32 v64, v64, v171
	v_mul_f32_e32 v64, v64, v178
	v_mul_f32_e32 v178, 0xbfb8aa3b, v178
	v_exp_f32_e32 v178, v178
	v_lshlrev_b64 v[98:99], 7, v[98:99]
	v_lshl_add_u64 v[98:99], s[34:35], 0, v[98:99]
	v_lshl_add_u64 v[98:99], v[98:99], 0, v[2:3]
	v_add_f32_e32 v178, 1.0, v178
	v_rcp_f32_e32 v178, v178
	v_mul_f32_e32 v48, v48, v171
	v_mul_f32_e32 v32, v32, v171
	v_mul_f32_e32 v16, v16, v171
	v_mul_f32_e32 v64, v64, v178
	v_bfe_u32 v178, v64, 16, 1
	v_add3_u32 v64, v64, v178, s63
	global_store_short_d16_hi v[98:99], v64, off
	v_lshlrev_b32_e32 v64, 16, v177
	v_mul_f32_e32 v48, v48, v64
	v_mul_f32_e32 v64, 0xbfb8aa3b, v64
	v_exp_f32_e32 v64, v64
	v_mul_f32_e32 v17, v17, v166
	v_mul_f32_e32 v18, v18, v161
	v_mul_f32_e32 v19, v19, v155
	v_add_f32_e32 v64, 1.0, v64
	v_rcp_f32_e32 v64, v64
	v_lshlrev_b64 v[14:15], 7, v[14:15]
	v_lshl_add_u64 v[14:15], s[34:35], 0, v[14:15]
	v_lshl_add_u64 v[14:15], v[14:15], 0, v[2:3]
	v_mul_f32_e32 v48, v48, v64
	v_bfe_u32 v64, v48, 16, 1
	v_add3_u32 v48, v48, v64, s63
	global_store_short_d16_hi v[98:99], v48, off offset:64
	s_waitcnt vmcnt(62)
	v_lshlrev_b32_e32 v48, 16, v176
	v_mul_f32_e32 v32, v32, v48
	v_mul_f32_e32 v48, 0xbfb8aa3b, v48
	v_exp_f32_e32 v48, v48
	v_add_co_u32_e32 v98, vcc, s93, v98
	v_lshlrev_b64 v[12:13], 7, v[12:13]
	v_add_f32_e32 v48, 1.0, v48
	v_rcp_f32_e32 v48, v48
	v_addc_co_u32_e32 v99, vcc, 0, v99, vcc
	v_lshl_add_u64 v[12:13], s[34:35], 0, v[12:13]
	v_mul_f32_e32 v32, v32, v48
	v_bfe_u32 v48, v32, 16, 1
	v_add3_u32 v32, v32, v48, s63
	global_store_short_d16_hi v[98:99], v32, off
	v_lshlrev_b32_e32 v32, 16, v175
	v_mul_f32_e32 v16, v16, v32
	v_mul_f32_e32 v32, 0xbfb8aa3b, v32
	v_exp_f32_e32 v32, v32
	v_lshl_add_u64 v[12:13], v[12:13], 0, v[2:3]
	v_lshlrev_b64 v[10:11], 7, v[10:11]
	v_lshl_add_u64 v[10:11], s[34:35], 0, v[10:11]
	v_add_f32_e32 v32, 1.0, v32
	v_rcp_f32_e32 v32, v32
	v_lshl_add_u64 v[10:11], v[10:11], 0, v[2:3]
	v_lshlrev_b64 v[8:9], 7, v[8:9]
	v_lshl_add_u64 v[8:9], s[34:35], 0, v[8:9]
	v_mul_f32_e32 v16, v16, v32
	v_bfe_u32 v32, v16, 16, 1
	v_add3_u32 v16, v16, v32, s63
	global_store_short_d16_hi v[98:99], v16, off offset:64
	s_waitcnt vmcnt(62)
	v_lshlrev_b32_e32 v16, 16, v174
	v_mul_f32_e32 v32, v65, v166
	v_mul_f32_e32 v32, v32, v16
	v_mul_f32_e32 v16, 0xbfb8aa3b, v16
	v_exp_f32_e32 v16, v16
	v_lshlrev_b64 v[64:65], 7, v[96:97]
	v_lshl_add_u64 v[64:65], s[34:35], 0, v[64:65]
	v_lshl_add_u64 v[64:65], v[64:65], 0, v[2:3]
	v_add_f32_e32 v16, 1.0, v16
	v_rcp_f32_e32 v16, v16
	v_lshl_add_u64 v[8:9], v[8:9], 0, v[2:3]
	v_lshlrev_b64 v[6:7], 7, v[6:7]
	v_lshl_add_u64 v[6:7], s[34:35], 0, v[6:7]
	v_mul_f32_e32 v16, v32, v16
	v_bfe_u32 v32, v16, 16, 1
	v_add3_u32 v16, v16, v32, s63
	global_store_short_d16_hi v[64:65], v16, off
	v_lshlrev_b32_e32 v16, 16, v173
	v_mul_f32_e32 v32, v49, v166
	v_mul_f32_e32 v32, v32, v16
	v_mul_f32_e32 v16, 0xbfb8aa3b, v16
	v_exp_f32_e32 v16, v16
	v_lshl_add_u64 v[6:7], v[6:7], 0, v[2:3]
	v_lshlrev_b64 v[4:5], 7, v[4:5]
	v_lshl_add_u64 v[4:5], s[34:35], 0, v[4:5]
	v_add_f32_e32 v16, 1.0, v16
	v_rcp_f32_e32 v16, v16
	v_readlane_b32 s0, v254, 14
	s_add_i32 s76, s76, s66
	s_add_i32 s75, s75, s0
	v_mul_f32_e32 v16, v32, v16
	v_bfe_u32 v32, v16, 16, 1
	v_add3_u32 v16, v16, v32, s63
	global_store_short_d16_hi v[64:65], v16, off offset:64
	s_waitcnt vmcnt(62)
	v_lshlrev_b32_e32 v16, 16, v172
	v_mul_f32_e32 v32, v33, v166
	v_mul_f32_e32 v32, v32, v16
	v_mul_f32_e32 v16, 0xbfb8aa3b, v16
	v_exp_f32_e32 v16, v16
	s_cmpk_gt_i32 s76, 0x3ff
	v_add_f32_e32 v16, 1.0, v16
	v_rcp_f32_e32 v16, v16
	s_nop 0
	v_mul_f32_e32 v16, v32, v16
	v_bfe_u32 v32, v16, 16, 1
	v_add3_u32 v16, v16, v32, s63
	v_add_co_u32_e32 v32, vcc, s93, v64
	s_nop 1
	v_addc_co_u32_e32 v33, vcc, 0, v65, vcc
	global_store_short_d16_hi v[32:33], v16, off
	v_lshlrev_b32_e32 v16, 16, v170
	v_mul_f32_e32 v17, v17, v16
	v_mul_f32_e32 v16, 0xbfb8aa3b, v16
	v_exp_f32_e32 v16, v16
	s_nop 0
	v_add_f32_e32 v16, 1.0, v16
	v_rcp_f32_e32 v16, v16
	s_nop 0
	v_mul_f32_e32 v16, v17, v16
	v_bfe_u32 v17, v16, 16, 1
	v_add3_u32 v16, v16, v17, s63
	global_store_short_d16_hi v[32:33], v16, off offset:64
	s_waitcnt vmcnt(62)
	v_lshlrev_b32_e32 v16, 16, v169
	v_mul_f32_e32 v17, v66, v161
	v_mul_f32_e32 v17, v17, v16
	v_mul_f32_e32 v16, 0xbfb8aa3b, v16
	v_exp_f32_e32 v16, v16
	v_mul_f32_e32 v33, v50, v161
	v_add_f32_e32 v16, 1.0, v16
	v_rcp_f32_e32 v16, v16
	s_nop 0
	v_mul_f32_e32 v16, v17, v16
	v_bfe_u32 v17, v16, 16, 1
	v_add3_u32 v32, v16, v17, s63
	v_lshlrev_b64 v[16:17], 7, v[94:95]
	v_lshl_add_u64 v[16:17], s[34:35], 0, v[16:17]
	v_lshl_add_u64 v[16:17], v[16:17], 0, v[2:3]
	global_store_short_d16_hi v[16:17], v32, off
	v_lshlrev_b32_e32 v32, 16, v168
	v_mul_f32_e32 v33, v33, v32
	v_mul_f32_e32 v32, 0xbfb8aa3b, v32
	v_exp_f32_e32 v32, v32
	s_nop 0
	v_add_f32_e32 v32, 1.0, v32
	v_rcp_f32_e32 v32, v32
	s_nop 0
	v_mul_f32_e32 v32, v33, v32
	v_bfe_u32 v33, v32, 16, 1
	v_add3_u32 v32, v32, v33, s63
	global_store_short_d16_hi v[16:17], v32, off offset:64
	s_waitcnt vmcnt(62)
	v_lshlrev_b32_e32 v32, 16, v167
	v_mul_f32_e32 v33, v34, v161
	v_mul_f32_e32 v33, v33, v32
	v_mul_f32_e32 v32, 0xbfb8aa3b, v32
	v_exp_f32_e32 v32, v32
	v_add_co_u32_e32 v16, vcc, s93, v16
	v_add_f32_e32 v32, 1.0, v32
	v_rcp_f32_e32 v32, v32
	v_addc_co_u32_e32 v17, vcc, 0, v17, vcc
	v_mul_f32_e32 v32, v33, v32
	v_bfe_u32 v33, v32, 16, 1
	v_add3_u32 v32, v32, v33, s63
	global_store_short_d16_hi v[16:17], v32, off
	v_lshlrev_b32_e32 v32, 16, v165
	v_mul_f32_e32 v18, v18, v32
	v_mul_f32_e32 v32, 0xbfb8aa3b, v32
	v_exp_f32_e32 v32, v32
	s_nop 0
	v_add_f32_e32 v32, 1.0, v32
	v_rcp_f32_e32 v32, v32
	s_nop 0
	v_mul_f32_e32 v18, v18, v32
	v_bfe_u32 v32, v18, 16, 1
	v_add3_u32 v18, v18, v32, s63
	global_store_short_d16_hi v[16:17], v18, off offset:64
	s_waitcnt vmcnt(62)
; __device__ __forceinline__ float bf2f(unsigned h) { return __uint_as_float(h << 16); }
; __device__ __forceinline__ unsigned f2bf(float f) { unsigned u = __float_as_uint(f); return (u + 0x7fffu + ((u >> 16) & 1u)) >> 16; }
; __device__ __forceinline__ int crow(int r, int hi) { return (r & 3) + 8 * (r >> 2) + 4 * hi; }
; __device__ __forceinline__ void na_unit3(char* lds, const bf16_t* __restrict__ Qp, const bf16_t* __restrict__ Knp, const bf16_t* __restrict__ Vp, ...
;     ...
;     for (int r = 0; r < 16; ++r) { const long trow = wid * QBLK + crow(r, hi);
; #pragma unroll
;       for (int d0 = 0; d0 < 4; ++d0) { const float z = bf2f(zr[r][d0]); const float v = o[d0][r] * rli[r];
;         const float g = v * z * __builtin_amdgcn_rcpf(1.f + __expf(-z));
;         Op[((size_t)(d0 >> 1) * M_TOK + trow) * 64 + (d0 & 1) * 32 + r32] = (bf16_t)f2bf(g); } } }
	v_lshlrev_b32_e32 v16, 16, v164
	v_mul_f32_e32 v17, v67, v155
	v_mul_f32_e32 v17, v17, v16
	v_mul_f32_e32 v16, 0xbfb8aa3b, v16
	v_exp_f32_e32 v16, v16
	v_mul_f32_e32 v32, v51, v155
	v_add_f32_e32 v16, 1.0, v16
	v_rcp_f32_e32 v16, v16
	s_nop 0
	v_mul_f32_e32 v16, v17, v16
	v_bfe_u32 v17, v16, 16, 1
	v_add3_u32 v18, v16, v17, s63
	v_lshlrev_b64 v[16:17], 7, v[92:93]
	v_lshl_add_u64 v[16:17], s[34:35], 0, v[16:17]
	v_lshl_add_u64 v[16:17], v[16:17], 0, v[2:3]
	global_store_short_d16_hi v[16:17], v18, off
	v_lshlrev_b32_e32 v18, 16, v163
	v_mul_f32_e32 v32, v32, v18
	v_mul_f32_e32 v18, 0xbfb8aa3b, v18
	v_exp_f32_e32 v18, v18
	s_nop 0
	v_add_f32_e32 v18, 1.0, v18
	v_rcp_f32_e32 v18, v18
	s_nop 0
	v_mul_f32_e32 v18, v32, v18
	v_bfe_u32 v32, v18, 16, 1
	v_add3_u32 v18, v18, v32, s63
	global_store_short_d16_hi v[16:17], v18, off offset:64
	s_waitcnt vmcnt(62)
	v_lshlrev_b32_e32 v18, 16, v162
	v_mul_f32_e32 v32, v35, v155
	v_mul_f32_e32 v32, v32, v18
	v_mul_f32_e32 v18, 0xbfb8aa3b, v18
	v_exp_f32_e32 v18, v18
	v_add_co_u32_e32 v16, vcc, s93, v16
	v_add_f32_e32 v18, 1.0, v18
	v_rcp_f32_e32 v18, v18
	v_addc_co_u32_e32 v17, vcc, 0, v17, vcc
	v_mul_f32_e32 v18, v32, v18
	v_bfe_u32 v32, v18, 16, 1
	v_add3_u32 v18, v18, v32, s63
	global_store_short_d16_hi v[16:17], v18, off
	v_lshlrev_b32_e32 v18, 16, v160
	v_mul_f32_e32 v19, v19, v18
	v_mul_f32_e32 v18, 0xbfb8aa3b, v18
	v_exp_f32_e32 v18, v18
	s_nop 0
	v_add_f32_e32 v18, 1.0, v18
	v_rcp_f32_e32 v18, v18
	s_nop 0
	v_mul_f32_e32 v18, v19, v18
	v_bfe_u32 v19, v18, 16, 1
	v_add3_u32 v18, v18, v19, s63
	global_store_short_d16_hi v[16:17], v18, off offset:64
	s_waitcnt vmcnt(62)
	v_lshlrev_b32_e32 v16, 16, v159
	v_mul_f32_e32 v17, v68, v149
	v_mul_f32_e32 v17, v17, v16
	v_mul_f32_e32 v16, 0xbfb8aa3b, v16
	v_exp_f32_e32 v16, v16
	v_mul_f32_e32 v19, v52, v149
	v_add_f32_e32 v16, 1.0, v16
	v_rcp_f32_e32 v16, v16
	s_nop 0
	v_mul_f32_e32 v16, v17, v16
	v_bfe_u32 v17, v16, 16, 1
	v_add3_u32 v18, v16, v17, s63
	v_lshlrev_b64 v[16:17], 7, v[90:91]
	v_lshl_add_u64 v[16:17], s[34:35], 0, v[16:17]
	v_lshl_add_u64 v[16:17], v[16:17], 0, v[2:3]
	global_store_short_d16_hi v[16:17], v18, off
	v_lshlrev_b32_e32 v18, 16, v158
	v_mul_f32_e32 v19, v19, v18
	v_mul_f32_e32 v18, 0xbfb8aa3b, v18
	v_exp_f32_e32 v18, v18
	s_nop 0
	v_add_f32_e32 v18, 1.0, v18
	v_rcp_f32_e32 v18, v18
	s_nop 0
	v_mul_f32_e32 v18, v19, v18
	v_bfe_u32 v19, v18, 16, 1
	v_add3_u32 v18, v18, v19, s63
	global_store_short_d16_hi v[16:17], v18, off offset:64
	s_waitcnt vmcnt(62)
	v_lshlrev_b32_e32 v18, 16, v157
	v_mul_f32_e32 v19, v36, v149
	v_mul_f32_e32 v19, v19, v18
	v_mul_f32_e32 v18, 0xbfb8aa3b, v18
	v_exp_f32_e32 v18, v18
	v_add_co_u32_e32 v16, vcc, s93, v16
	v_add_f32_e32 v18, 1.0, v18
	v_rcp_f32_e32 v18, v18
	v_addc_co_u32_e32 v17, vcc, 0, v17, vcc
	v_mul_f32_e32 v18, v19, v18
	v_bfe_u32 v19, v18, 16, 1
	v_add3_u32 v18, v18, v19, s63
	global_store_short_d16_hi v[16:17], v18, off
	v_lshlrev_b32_e32 v18, 16, v156
	v_mul_f32_e32 v19, v20, v149
	v_mul_f32_e32 v19, v19, v18
	v_mul_f32_e32 v18, 0xbfb8aa3b, v18
	v_exp_f32_e32 v18, v18
	s_nop 0
	v_add_f32_e32 v18, 1.0, v18
	v_rcp_f32_e32 v18, v18
	s_nop 0
	v_mul_f32_e32 v18, v19, v18
	v_bfe_u32 v19, v18, 16, 1
	v_add3_u32 v18, v18, v19, s63
	global_store_short_d16_hi v[16:17], v18, off offset:64
	s_waitcnt vmcnt(62)
	v_lshlrev_b32_e32 v16, 16, v154
	v_mul_f32_e32 v17, v69, v144
	v_mul_f32_e32 v17, v17, v16
	v_mul_f32_e32 v16, 0xbfb8aa3b, v16
	v_exp_f32_e32 v16, v16
	v_mul_f32_e32 v19, v53, v144
	v_add_f32_e32 v16, 1.0, v16
	v_rcp_f32_e32 v16, v16
	s_nop 0
	v_mul_f32_e32 v16, v17, v16
	v_bfe_u32 v17, v16, 16, 1
	v_add3_u32 v18, v16, v17, s63
	v_lshlrev_b64 v[16:17], 7, v[88:89]
	v_lshl_add_u64 v[16:17], s[34:35], 0, v[16:17]
	v_lshl_add_u64 v[16:17], v[16:17], 0, v[2:3]
	global_store_short_d16_hi v[16:17], v18, off
	v_lshlrev_b32_e32 v18, 16, v153
	v_mul_f32_e32 v19, v19, v18
	v_mul_f32_e32 v18, 0xbfb8aa3b, v18
	v_exp_f32_e32 v18, v18
	s_nop 0
	v_add_f32_e32 v18, 1.0, v18
	v_rcp_f32_e32 v18, v18
	s_nop 0
	v_mul_f32_e32 v18, v19, v18
	v_bfe_u32 v19, v18, 16, 1
	v_add3_u32 v18, v18, v19, s63
	global_store_short_d16_hi v[16:17], v18, off offset:64
	s_waitcnt vmcnt(62)
	v_lshlrev_b32_e32 v18, 16, v152
	v_mul_f32_e32 v19, v37, v144
	v_mul_f32_e32 v19, v19, v18
	v_mul_f32_e32 v18, 0xbfb8aa3b, v18
	v_exp_f32_e32 v18, v18
	v_add_co_u32_e32 v16, vcc, s93, v16
	v_add_f32_e32 v18, 1.0, v18
	v_rcp_f32_e32 v18, v18
	v_addc_co_u32_e32 v17, vcc, 0, v17, vcc
	v_mul_f32_e32 v18, v19, v18
	v_bfe_u32 v19, v18, 16, 1
	v_add3_u32 v18, v18, v19, s63
	global_store_short_d16_hi v[16:17], v18, off
	v_lshlrev_b32_e32 v18, 16, v151
	v_mul_f32_e32 v19, v21, v144
	v_mul_f32_e32 v19, v19, v18
	v_mul_f32_e32 v18, 0xbfb8aa3b, v18
	v_exp_f32_e32 v18, v18
	s_nop 0
	v_add_f32_e32 v18, 1.0, v18
	v_rcp_f32_e32 v18, v18
	s_nop 0
	v_mul_f32_e32 v18, v19, v18
	v_bfe_u32 v19, v18, 16, 1
	v_add3_u32 v18, v18, v19, s63
	global_store_short_d16_hi v[16:17], v18, off offset:64
	s_waitcnt vmcnt(62)
	v_lshlrev_b32_e32 v16, 16, v150
	v_mul_f32_e32 v17, v70, v139
	v_mul_f32_e32 v17, v17, v16
	v_mul_f32_e32 v16, 0xbfb8aa3b, v16
	v_exp_f32_e32 v16, v16
	v_mul_f32_e32 v19, v54, v139
	v_add_f32_e32 v16, 1.0, v16
	v_rcp_f32_e32 v16, v16
	s_nop 0
	v_mul_f32_e32 v16, v17, v16
	v_bfe_u32 v17, v16, 16, 1
	v_add3_u32 v18, v16, v17, s63
	v_lshlrev_b64 v[16:17], 7, v[86:87]
	v_lshl_add_u64 v[16:17], s[34:35], 0, v[16:17]
	v_lshl_add_u64 v[16:17], v[16:17], 0, v[2:3]
	global_store_short_d16_hi v[16:17], v18, off
	v_lshlrev_b32_e32 v18, 16, v148
	v_mul_f32_e32 v19, v19, v18
	v_mul_f32_e32 v18, 0xbfb8aa3b, v18
	v_exp_f32_e32 v18, v18
	s_nop 0
	v_add_f32_e32 v18, 1.0, v18
	v_rcp_f32_e32 v18, v18
	s_nop 0
	v_mul_f32_e32 v18, v19, v18
	v_bfe_u32 v19, v18, 16, 1
	v_add3_u32 v18, v18, v19, s63
	global_store_short_d16_hi v[16:17], v18, off offset:64
	s_waitcnt vmcnt(62)
; __device__ __forceinline__ float bf2f(unsigned h) { return __uint_as_float(h << 16); }
; __device__ __forceinline__ unsigned f2bf(float f) { unsigned u = __float_as_uint(f); return (u + 0x7fffu + ((u >> 16) & 1u)) >> 16; }
; __device__ __forceinline__ int crow(int r, int hi) { return (r & 3) + 8 * (r >> 2) + 4 * hi; }
; __device__ __forceinline__ void na_unit3(char* lds, const bf16_t* __restrict__ Qp, const bf16_t* __restrict__ Knp, const bf16_t* __restrict__ Vp, ...
;     ...
;     for (int r = 0; r < 16; ++r) { const long trow = wid * QBLK + crow(r, hi);
; #pragma unroll
;       for (int d0 = 0; d0 < 4; ++d0) { const float z = bf2f(zr[r][d0]); const float v = o[d0][r] * rli[r];
;         const float g = v * z * __builtin_amdgcn_rcpf(1.f + __expf(-z));
;         Op[((size_t)(d0 >> 1) * M_TOK + trow) * 64 + (d0 & 1) * 32 + r32] = (bf16_t)f2bf(g); } } }
	v_lshlrev_b32_e32 v18, 16, v147
	v_mul_f32_e32 v19, v38, v139
	v_mul_f32_e32 v19, v19, v18
	v_mul_f32_e32 v18, 0xbfb8aa3b, v18
	v_exp_f32_e32 v18, v18
	v_add_co_u32_e32 v16, vcc, s93, v16
	v_add_f32_e32 v18, 1.0, v18
	v_rcp_f32_e32 v18, v18
	v_addc_co_u32_e32 v17, vcc, 0, v17, vcc
	v_mul_f32_e32 v18, v19, v18
	v_bfe_u32 v19, v18, 16, 1
	v_add3_u32 v18, v18, v19, s63
	global_store_short_d16_hi v[16:17], v18, off
	v_lshlrev_b32_e32 v18, 16, v146
	v_mul_f32_e32 v19, v22, v139
	v_mul_f32_e32 v19, v19, v18
	v_mul_f32_e32 v18, 0xbfb8aa3b, v18
	v_exp_f32_e32 v18, v18
	s_nop 0
	v_add_f32_e32 v18, 1.0, v18
	v_rcp_f32_e32 v18, v18
	s_nop 0
	v_mul_f32_e32 v18, v19, v18
	v_bfe_u32 v19, v18, 16, 1
	v_add3_u32 v18, v18, v19, s63
	global_store_short_d16_hi v[16:17], v18, off offset:64
	s_waitcnt vmcnt(62)
	v_lshlrev_b32_e32 v16, 16, v145
	v_mul_f32_e32 v17, v71, v133
	v_mul_f32_e32 v17, v17, v16
	v_mul_f32_e32 v16, 0xbfb8aa3b, v16
	v_exp_f32_e32 v16, v16
	v_mul_f32_e32 v19, v55, v133
	v_add_f32_e32 v16, 1.0, v16
	v_rcp_f32_e32 v16, v16
	s_nop 0
	v_mul_f32_e32 v16, v17, v16
	v_bfe_u32 v17, v16, 16, 1
	v_add3_u32 v18, v16, v17, s63
	v_lshlrev_b64 v[16:17], 7, v[84:85]
	v_lshl_add_u64 v[16:17], s[34:35], 0, v[16:17]
	v_lshl_add_u64 v[16:17], v[16:17], 0, v[2:3]
	global_store_short_d16_hi v[16:17], v18, off
	v_lshlrev_b32_e32 v18, 16, v143
	v_mul_f32_e32 v19, v19, v18
	v_mul_f32_e32 v18, 0xbfb8aa3b, v18
	v_exp_f32_e32 v18, v18
	s_nop 0
	v_add_f32_e32 v18, 1.0, v18
	v_rcp_f32_e32 v18, v18
	s_nop 0
	v_mul_f32_e32 v18, v19, v18
	v_bfe_u32 v19, v18, 16, 1
	v_add3_u32 v18, v18, v19, s63
	global_store_short_d16_hi v[16:17], v18, off offset:64
	s_waitcnt vmcnt(62)
	v_lshlrev_b32_e32 v18, 16, v142
	v_mul_f32_e32 v19, v39, v133
	v_mul_f32_e32 v19, v19, v18
	v_mul_f32_e32 v18, 0xbfb8aa3b, v18
	v_exp_f32_e32 v18, v18
	v_add_co_u32_e32 v16, vcc, s93, v16
	v_add_f32_e32 v18, 1.0, v18
	v_rcp_f32_e32 v18, v18
	v_addc_co_u32_e32 v17, vcc, 0, v17, vcc
	v_mul_f32_e32 v18, v19, v18
	v_bfe_u32 v19, v18, 16, 1
	v_add3_u32 v18, v18, v19, s63
	global_store_short_d16_hi v[16:17], v18, off
	v_lshlrev_b32_e32 v18, 16, v141
	v_mul_f32_e32 v19, v23, v133
	v_mul_f32_e32 v19, v19, v18
	v_mul_f32_e32 v18, 0xbfb8aa3b, v18
	v_exp_f32_e32 v18, v18
	s_nop 0
	v_add_f32_e32 v18, 1.0, v18
	v_rcp_f32_e32 v18, v18
	s_nop 0
	v_mul_f32_e32 v18, v19, v18
	v_bfe_u32 v19, v18, 16, 1
	v_add3_u32 v18, v18, v19, s63
	global_store_short_d16_hi v[16:17], v18, off offset:64
	s_waitcnt vmcnt(62)
	v_lshlrev_b32_e32 v16, 16, v140
	v_mul_f32_e32 v17, v72, v128
	v_mul_f32_e32 v17, v17, v16
	v_mul_f32_e32 v16, 0xbfb8aa3b, v16
	v_exp_f32_e32 v16, v16
	v_mul_f32_e32 v19, v56, v128
	v_add_f32_e32 v16, 1.0, v16
	v_rcp_f32_e32 v16, v16
	s_nop 0
	v_mul_f32_e32 v16, v17, v16
	v_bfe_u32 v17, v16, 16, 1
	v_add3_u32 v18, v16, v17, s63
	v_lshlrev_b64 v[16:17], 7, v[82:83]
	v_lshl_add_u64 v[16:17], s[34:35], 0, v[16:17]
	v_lshl_add_u64 v[16:17], v[16:17], 0, v[2:3]
	global_store_short_d16_hi v[16:17], v18, off
	v_lshlrev_b32_e32 v18, 16, v138
	v_mul_f32_e32 v19, v19, v18
	v_mul_f32_e32 v18, 0xbfb8aa3b, v18
	v_exp_f32_e32 v18, v18
	s_nop 0
	v_add_f32_e32 v18, 1.0, v18
	v_rcp_f32_e32 v18, v18
	s_nop 0
	v_mul_f32_e32 v18, v19, v18
	v_bfe_u32 v19, v18, 16, 1
	v_add3_u32 v18, v18, v19, s63
	global_store_short_d16_hi v[16:17], v18, off offset:64
	s_waitcnt vmcnt(62)
	v_lshlrev_b32_e32 v18, 16, v137
	v_mul_f32_e32 v19, v40, v128
	v_mul_f32_e32 v19, v19, v18
	v_mul_f32_e32 v18, 0xbfb8aa3b, v18
	v_exp_f32_e32 v18, v18
	v_add_co_u32_e32 v16, vcc, s93, v16
	v_add_f32_e32 v18, 1.0, v18
	v_rcp_f32_e32 v18, v18
	v_addc_co_u32_e32 v17, vcc, 0, v17, vcc
	v_mul_f32_e32 v18, v19, v18
	v_bfe_u32 v19, v18, 16, 1
	v_add3_u32 v18, v18, v19, s63
	global_store_short_d16_hi v[16:17], v18, off
	v_lshlrev_b32_e32 v18, 16, v136
	v_mul_f32_e32 v19, v24, v128
	v_mul_f32_e32 v19, v19, v18
	v_mul_f32_e32 v18, 0xbfb8aa3b, v18
	v_exp_f32_e32 v18, v18
	s_nop 0
	v_add_f32_e32 v18, 1.0, v18
	v_rcp_f32_e32 v18, v18
	s_nop 0
	v_mul_f32_e32 v18, v19, v18
	v_bfe_u32 v19, v18, 16, 1
	v_add3_u32 v18, v18, v19, s63
	global_store_short_d16_hi v[16:17], v18, off offset:64
	s_waitcnt vmcnt(62)
	v_lshlrev_b32_e32 v16, 16, v135
	v_mul_f32_e32 v17, v73, v122
	v_mul_f32_e32 v17, v17, v16
	v_mul_f32_e32 v16, 0xbfb8aa3b, v16
	v_exp_f32_e32 v16, v16
	v_mul_f32_e32 v19, v57, v122
	v_add_f32_e32 v16, 1.0, v16
	v_rcp_f32_e32 v16, v16
	s_nop 0
	v_mul_f32_e32 v16, v17, v16
	v_bfe_u32 v17, v16, 16, 1
	v_add3_u32 v18, v16, v17, s63
	v_lshlrev_b64 v[16:17], 7, v[80:81]
	v_lshl_add_u64 v[16:17], s[34:35], 0, v[16:17]
	v_lshl_add_u64 v[16:17], v[16:17], 0, v[2:3]
	global_store_short_d16_hi v[16:17], v18, off
	v_lshlrev_b32_e32 v18, 16, v134
	v_mul_f32_e32 v19, v19, v18
	v_mul_f32_e32 v18, 0xbfb8aa3b, v18
	v_exp_f32_e32 v18, v18
	v_lshl_add_u64 v[2:3], v[4:5], 0, v[2:3]
	s_waitcnt vmcnt(39)
	v_lshlrev_b32_e32 v4, 16, v104
	v_mul_f32_e32 v5, v63, v1
	v_add_f32_e32 v18, 1.0, v18
	v_rcp_f32_e32 v18, v18
	v_mul_f32_e32 v5, v5, v4
	v_mul_f32_e32 v4, 0xbfb8aa3b, v4
	v_exp_f32_e32 v4, v4
	v_mul_f32_e32 v18, v19, v18
	v_bfe_u32 v19, v18, 16, 1
	v_add3_u32 v18, v18, v19, s63
	global_store_short_d16_hi v[16:17], v18, off offset:64
	v_lshlrev_b32_e32 v18, 16, v132
	v_mul_f32_e32 v19, v41, v122
	v_mul_f32_e32 v19, v19, v18
	v_mul_f32_e32 v18, 0xbfb8aa3b, v18
	v_exp_f32_e32 v18, v18
	v_add_co_u32_e32 v16, vcc, s93, v16
	v_add_f32_e32 v4, 1.0, v4
	v_add_f32_e32 v18, 1.0, v18
	v_rcp_f32_e32 v18, v18
	v_addc_co_u32_e32 v17, vcc, 0, v17, vcc
	v_rcp_f32_e32 v4, v4
	v_mul_f32_e32 v18, v19, v18
	v_bfe_u32 v19, v18, 16, 1
	v_add3_u32 v18, v18, v19, s63
	global_store_short_d16_hi v[16:17], v18, off
	v_lshlrev_b32_e32 v18, 16, v131
	v_mul_f32_e32 v19, v25, v122
	v_mul_f32_e32 v19, v19, v18
	v_mul_f32_e32 v18, 0xbfb8aa3b, v18
	v_exp_f32_e32 v18, v18
	v_mul_f32_e32 v4, v5, v4
	v_bfe_u32 v5, v4, 16, 1
	v_add3_u32 v4, v4, v5, s63
	v_add_f32_e32 v18, 1.0, v18
	v_rcp_f32_e32 v18, v18
	global_store_short_d16_hi v[2:3], v4, off offset:64
	s_waitcnt vmcnt(41)
; __device__ __forceinline__ float bf2f(unsigned h) { return __uint_as_float(h << 16); }
; __device__ __forceinline__ unsigned f2bf(float f) { unsigned u = __float_as_uint(f); return (u + 0x7fffu + ((u >> 16) & 1u)) >> 16; }
; __device__ __forceinline__ int crow(int r, int hi) { return (r & 3) + 8 * (r >> 2) + 4 * hi; }
; __device__ __forceinline__ void na_unit3(char* lds, const bf16_t* __restrict__ Qp, const bf16_t* __restrict__ Knp, const bf16_t* __restrict__ Vp, ...
;     ...
;     for (int r = 0; r < 16; ++r) { const long trow = wid * QBLK + crow(r, hi);
; #pragma unroll
;       for (int d0 = 0; d0 < 4; ++d0) { const float z = bf2f(zr[r][d0]); const float v = o[d0][r] * rli[r];
;         const float g = v * z * __builtin_amdgcn_rcpf(1.f + __expf(-z));
;         Op[((size_t)(d0 >> 1) * M_TOK + trow) * 64 + (d0 & 1) * 32 + r32] = (bf16_t)f2bf(g); } } }
	v_lshlrev_b32_e32 v4, 16, v101
	v_mul_f32_e32 v5, v47, v1
	v_mul_f32_e32 v18, v19, v18
	v_bfe_u32 v19, v18, 16, 1
	v_add3_u32 v18, v18, v19, s63
	global_store_short_d16_hi v[16:17], v18, off offset:64
	v_lshlrev_b32_e32 v16, 16, v130
	v_mul_f32_e32 v17, v74, v117
	v_mul_f32_e32 v17, v17, v16
	v_mul_f32_e32 v16, 0xbfb8aa3b, v16
	v_exp_f32_e32 v16, v16
	v_mul_f32_e32 v5, v5, v4
	v_mul_f32_e32 v4, 0xbfb8aa3b, v4
	v_exp_f32_e32 v4, v4
	v_add_f32_e32 v16, 1.0, v16
	v_rcp_f32_e32 v16, v16
	v_add_f32_e32 v4, 1.0, v4
	v_rcp_f32_e32 v4, v4
	v_mul_f32_e32 v16, v17, v16
	v_bfe_u32 v17, v16, 16, 1
	v_add3_u32 v16, v16, v17, s63
	global_store_short_d16_hi v[14:15], v16, off
	v_lshlrev_b32_e32 v16, 16, v129
	v_mul_f32_e32 v17, v58, v117
	v_mul_f32_e32 v17, v17, v16
	v_mul_f32_e32 v16, 0xbfb8aa3b, v16
	v_exp_f32_e32 v16, v16
	v_mul_f32_e32 v4, v5, v4
	v_bfe_u32 v5, v4, 16, 1
	v_add3_u32 v4, v4, v5, s63
	v_add_f32_e32 v16, 1.0, v16
	v_rcp_f32_e32 v16, v16
	s_nop 0
	v_mul_f32_e32 v16, v17, v16
	v_bfe_u32 v17, v16, 16, 1
	v_add3_u32 v16, v16, v17, s63
	global_store_short_d16_hi v[14:15], v16, off offset:64
	v_lshlrev_b32_e32 v16, 16, v127
	v_mul_f32_e32 v17, v42, v117
	v_mul_f32_e32 v17, v17, v16
	v_mul_f32_e32 v16, 0xbfb8aa3b, v16
	v_exp_f32_e32 v16, v16
	v_add_co_u32_e32 v14, vcc, s93, v14
	v_add_f32_e32 v16, 1.0, v16
	v_rcp_f32_e32 v16, v16
	v_addc_co_u32_e32 v15, vcc, 0, v15, vcc
	v_mul_f32_e32 v16, v17, v16
	v_bfe_u32 v17, v16, 16, 1
	v_add3_u32 v16, v16, v17, s63
	global_store_short_d16_hi v[14:15], v16, off
	v_lshlrev_b32_e32 v16, 16, v126
	v_mul_f32_e32 v17, v26, v117
	v_mul_f32_e32 v17, v17, v16
	v_mul_f32_e32 v16, 0xbfb8aa3b, v16
	v_exp_f32_e32 v16, v16
	s_nop 0
	v_add_f32_e32 v16, 1.0, v16
	v_rcp_f32_e32 v16, v16
	s_nop 0
	v_mul_f32_e32 v16, v17, v16
	v_bfe_u32 v17, v16, 16, 1
	v_add3_u32 v16, v16, v17, s63
	global_store_short_d16_hi v[14:15], v16, off offset:64
	v_lshlrev_b32_e32 v14, 16, v125
	v_mul_f32_e32 v15, v75, v111
	v_mul_f32_e32 v15, v15, v14
	v_mul_f32_e32 v14, 0xbfb8aa3b, v14
	v_exp_f32_e32 v14, v14
	s_nop 0
	v_add_f32_e32 v14, 1.0, v14
	v_rcp_f32_e32 v14, v14
	s_nop 0
	v_mul_f32_e32 v14, v15, v14
	v_bfe_u32 v15, v14, 16, 1
	v_add3_u32 v14, v14, v15, s63
	global_store_short_d16_hi v[12:13], v14, off
	v_lshlrev_b32_e32 v14, 16, v124
	v_mul_f32_e32 v15, v59, v111
	v_mul_f32_e32 v15, v15, v14
	v_mul_f32_e32 v14, 0xbfb8aa3b, v14
	v_exp_f32_e32 v14, v14
	s_nop 0
	v_add_f32_e32 v14, 1.0, v14
	v_rcp_f32_e32 v14, v14
	s_nop 0
	v_mul_f32_e32 v14, v15, v14
	v_bfe_u32 v15, v14, 16, 1
	v_add3_u32 v14, v14, v15, s63
	global_store_short_d16_hi v[12:13], v14, off offset:64
	v_lshlrev_b32_e32 v14, 16, v123
	v_mul_f32_e32 v15, v43, v111
	v_mul_f32_e32 v15, v15, v14
	v_mul_f32_e32 v14, 0xbfb8aa3b, v14
	v_exp_f32_e32 v14, v14
	v_add_co_u32_e32 v12, vcc, s93, v12
	v_add_f32_e32 v14, 1.0, v14
	v_rcp_f32_e32 v14, v14
	v_addc_co_u32_e32 v13, vcc, 0, v13, vcc
	v_mul_f32_e32 v14, v15, v14
	v_bfe_u32 v15, v14, 16, 1
	v_add3_u32 v14, v14, v15, s63
	global_store_short_d16_hi v[12:13], v14, off
	v_lshlrev_b32_e32 v14, 16, v121
	v_mul_f32_e32 v15, v27, v111
	v_mul_f32_e32 v15, v15, v14
	v_mul_f32_e32 v14, 0xbfb8aa3b, v14
	v_exp_f32_e32 v14, v14
	s_nop 0
	v_add_f32_e32 v14, 1.0, v14
	v_rcp_f32_e32 v14, v14
	s_nop 0
	v_mul_f32_e32 v14, v15, v14
	v_bfe_u32 v15, v14, 16, 1
	v_add3_u32 v14, v14, v15, s63
	global_store_short_d16_hi v[12:13], v14, off offset:64
	v_lshlrev_b32_e32 v12, 16, v120
	v_mul_f32_e32 v13, v76, v105
	v_mul_f32_e32 v13, v13, v12
	v_mul_f32_e32 v12, 0xbfb8aa3b, v12
	v_exp_f32_e32 v12, v12
	s_nop 0
	v_add_f32_e32 v12, 1.0, v12
	v_rcp_f32_e32 v12, v12
	s_nop 0
	v_mul_f32_e32 v12, v13, v12
	v_bfe_u32 v13, v12, 16, 1
	v_add3_u32 v12, v12, v13, s63
	global_store_short_d16_hi v[10:11], v12, off
	v_lshlrev_b32_e32 v12, 16, v119
	v_mul_f32_e32 v13, v60, v105
	v_mul_f32_e32 v13, v13, v12
	v_mul_f32_e32 v12, 0xbfb8aa3b, v12
	v_exp_f32_e32 v12, v12
	s_nop 0
	v_add_f32_e32 v12, 1.0, v12
	v_rcp_f32_e32 v12, v12
	s_nop 0
	v_mul_f32_e32 v12, v13, v12
	v_bfe_u32 v13, v12, 16, 1
	v_add3_u32 v12, v12, v13, s63
	global_store_short_d16_hi v[10:11], v12, off offset:64
	v_lshlrev_b32_e32 v12, 16, v118
	v_mul_f32_e32 v13, v44, v105
	v_mul_f32_e32 v13, v13, v12
	v_mul_f32_e32 v12, 0xbfb8aa3b, v12
	v_exp_f32_e32 v12, v12
	v_add_co_u32_e32 v10, vcc, s93, v10
	v_add_f32_e32 v12, 1.0, v12
; __device__ __forceinline__ float bf2f(unsigned h) { return __uint_as_float(h << 16); }
; __device__ __forceinline__ unsigned f2bf(float f) { unsigned u = __float_as_uint(f); return (u + 0x7fffu + ((u >> 16) & 1u)) >> 16; }
; __device__ __forceinline__ int crow(int r, int hi) { return (r & 3) + 8 * (r >> 2) + 4 * hi; }
; __device__ __forceinline__ void na_unit3(char* lds, const bf16_t* __restrict__ Qp, const bf16_t* __restrict__ Knp, const bf16_t* __restrict__ Vp, ...
;     ...
;     for (int r = 0; r < 16; ++r) { const long trow = wid * QBLK + crow(r, hi);
; #pragma unroll
;       for (int d0 = 0; d0 < 4; ++d0) { const float z = bf2f(zr[r][d0]); const float v = o[d0][r] * rli[r];
;         const float g = v * z * __builtin_amdgcn_rcpf(1.f + __expf(-z));
;         Op[((size_t)(d0 >> 1) * M_TOK + trow) * 64 + (d0 & 1) * 32 + r32] = (bf16_t)f2bf(g); } } }
;   asm volatile("s_waitcnt vmcnt(0) lgkmcnt(0)\n\ts_barrier" ::: "memory");
	v_rcp_f32_e32 v12, v12
	v_addc_co_u32_e32 v11, vcc, 0, v11, vcc
	v_mul_f32_e32 v12, v13, v12
	v_bfe_u32 v13, v12, 16, 1
	v_add3_u32 v12, v12, v13, s63
	global_store_short_d16_hi v[10:11], v12, off
	v_lshlrev_b32_e32 v12, 16, v116
	v_mul_f32_e32 v13, v28, v105
	v_mul_f32_e32 v13, v13, v12
	v_mul_f32_e32 v12, 0xbfb8aa3b, v12
	v_exp_f32_e32 v12, v12
	s_nop 0
	v_add_f32_e32 v12, 1.0, v12
	v_rcp_f32_e32 v12, v12
	s_nop 0
	v_mul_f32_e32 v12, v13, v12
	v_bfe_u32 v13, v12, 16, 1
	v_add3_u32 v12, v12, v13, s63
	global_store_short_d16_hi v[10:11], v12, off offset:64
	v_lshlrev_b32_e32 v10, 16, v115
	v_mul_f32_e32 v11, v77, v103
	v_mul_f32_e32 v11, v11, v10
	v_mul_f32_e32 v10, 0xbfb8aa3b, v10
	v_exp_f32_e32 v10, v10
	s_nop 0
	v_add_f32_e32 v10, 1.0, v10
	v_rcp_f32_e32 v10, v10
	s_nop 0
	v_mul_f32_e32 v10, v11, v10
	v_bfe_u32 v11, v10, 16, 1
	v_add3_u32 v10, v10, v11, s63
	global_store_short_d16_hi v[8:9], v10, off
	v_lshlrev_b32_e32 v10, 16, v114
	v_mul_f32_e32 v11, v61, v103
	v_mul_f32_e32 v11, v11, v10
	v_mul_f32_e32 v10, 0xbfb8aa3b, v10
	v_exp_f32_e32 v10, v10
	s_nop 0
	v_add_f32_e32 v10, 1.0, v10
	v_rcp_f32_e32 v10, v10
	s_nop 0
	v_mul_f32_e32 v10, v11, v10
	v_bfe_u32 v11, v10, 16, 1
	v_add3_u32 v10, v10, v11, s63
	global_store_short_d16_hi v[8:9], v10, off offset:64
	v_lshlrev_b32_e32 v10, 16, v113
	v_mul_f32_e32 v11, v45, v103
	v_mul_f32_e32 v11, v11, v10
	v_mul_f32_e32 v10, 0xbfb8aa3b, v10
	v_exp_f32_e32 v10, v10
	v_add_co_u32_e32 v8, vcc, s93, v8
	v_add_f32_e32 v10, 1.0, v10
	v_rcp_f32_e32 v10, v10
	v_addc_co_u32_e32 v9, vcc, 0, v9, vcc
	v_mul_f32_e32 v10, v11, v10
	v_bfe_u32 v11, v10, 16, 1
	v_add3_u32 v10, v10, v11, s63
	global_store_short_d16_hi v[8:9], v10, off
	v_lshlrev_b32_e32 v10, 16, v112
	v_mul_f32_e32 v11, v29, v103
	v_mul_f32_e32 v11, v11, v10
	v_mul_f32_e32 v10, 0xbfb8aa3b, v10
	v_exp_f32_e32 v10, v10
	s_nop 0
	v_add_f32_e32 v10, 1.0, v10
	v_rcp_f32_e32 v10, v10
	s_nop 0
	v_mul_f32_e32 v10, v11, v10
	v_bfe_u32 v11, v10, 16, 1
	v_add3_u32 v10, v10, v11, s63
	global_store_short_d16_hi v[8:9], v10, off offset:64
	v_lshlrev_b32_e32 v8, 16, v110
	v_mul_f32_e32 v9, v78, v102
	v_mul_f32_e32 v9, v9, v8
	v_mul_f32_e32 v8, 0xbfb8aa3b, v8
	v_exp_f32_e32 v8, v8
	s_nop 0
	v_add_f32_e32 v8, 1.0, v8
	v_rcp_f32_e32 v8, v8
	s_nop 0
	v_mul_f32_e32 v8, v9, v8
	v_bfe_u32 v9, v8, 16, 1
	v_add3_u32 v8, v8, v9, s63
	global_store_short_d16_hi v[6:7], v8, off
	v_lshlrev_b32_e32 v8, 16, v109
	v_mul_f32_e32 v9, v62, v102
	v_mul_f32_e32 v9, v9, v8
	v_mul_f32_e32 v8, 0xbfb8aa3b, v8
	v_exp_f32_e32 v8, v8
	s_nop 0
	v_add_f32_e32 v8, 1.0, v8
	v_rcp_f32_e32 v8, v8
	s_nop 0
	v_mul_f32_e32 v8, v9, v8
	v_bfe_u32 v9, v8, 16, 1
	v_add3_u32 v8, v8, v9, s63
	global_store_short_d16_hi v[6:7], v8, off offset:64
	v_lshlrev_b32_e32 v8, 16, v108
	v_mul_f32_e32 v9, v46, v102
	v_mul_f32_e32 v9, v9, v8
	v_mul_f32_e32 v8, 0xbfb8aa3b, v8
	v_exp_f32_e32 v8, v8
	v_add_co_u32_e32 v6, vcc, s93, v6
	v_add_f32_e32 v8, 1.0, v8
	v_rcp_f32_e32 v8, v8
	v_addc_co_u32_e32 v7, vcc, 0, v7, vcc
	v_mul_f32_e32 v8, v9, v8
	v_bfe_u32 v9, v8, 16, 1
	v_add3_u32 v8, v8, v9, s63
	global_store_short_d16_hi v[6:7], v8, off
	v_lshlrev_b32_e32 v8, 16, v107
	v_mul_f32_e32 v9, v30, v102
	v_mul_f32_e32 v9, v9, v8
	v_mul_f32_e32 v8, 0xbfb8aa3b, v8
	v_exp_f32_e32 v8, v8
	s_nop 0
	v_add_f32_e32 v8, 1.0, v8
	v_rcp_f32_e32 v8, v8
	s_nop 0
	v_mul_f32_e32 v8, v9, v8
	v_bfe_u32 v9, v8, 16, 1
	v_add3_u32 v8, v8, v9, s63
	global_store_short_d16_hi v[6:7], v8, off offset:64
	v_lshlrev_b32_e32 v6, 16, v106
	v_mul_f32_e32 v7, v79, v1
	v_mul_f32_e32 v7, v7, v6
	v_mul_f32_e32 v6, 0xbfb8aa3b, v6
	v_exp_f32_e32 v6, v6
	v_mul_f32_e32 v1, v31, v1
	v_add_f32_e32 v6, 1.0, v6
	v_rcp_f32_e32 v6, v6
	s_nop 0
	v_mul_f32_e32 v6, v7, v6
	v_bfe_u32 v7, v6, 16, 1
	v_add3_u32 v6, v6, v7, s63
	global_store_short_d16_hi v[2:3], v6, off
	v_add_co_u32_e32 v2, vcc, s93, v2
	s_nop 1
	v_addc_co_u32_e32 v3, vcc, 0, v3, vcc
	global_store_short_d16_hi v[2:3], v4, off
	s_waitcnt vmcnt(62)
	v_lshlrev_b32_e32 v4, 16, v100
	v_mul_f32_e32 v1, v1, v4
	v_mul_f32_e32 v4, 0xbfb8aa3b, v4
	v_exp_f32_e32 v4, v4
	s_nop 0
	v_add_f32_e32 v4, 1.0, v4
	v_rcp_f32_e32 v4, v4
	s_nop 0
	v_mul_f32_e32 v1, v1, v4
	v_bfe_u32 v4, v1, 16, 1
	v_add3_u32 v1, v1, v4, s63
	global_store_short_d16_hi v[2:3], v1, off offset:64
	s_waitcnt lgkmcnt(0)
	s_barrier
	s_cbranch_scc1 .LBB0_352
